# nt also on the converted bf16 weight stores of step 3 (first read hundreds of us to ms later)
# baseline (speedup 1.0000x reference)
; #define LAS __attribute__((address_space(3)))
; __device__ __forceinline__ unsigned cvt_pk_bf16(float lo, float hi) { f32x2 v = {lo, hi}; bf16x2_t b = __builtin_convertvector(v, bf16x2_t); return __builtin_bit_cast(unsigned, b); }
; __device__ __forceinline__ void cvt_tile(const float* W, int ldw, int nvalid, int k0, int n0, bf16_t* WT, int K, int map, int rows_cap, LAS unsigned char* T, int tid, const float* gvec) {
;     ...
;     const int phys = w ^ (lane & 7);
; #pragma unroll
;     for (int hh = 0; hh < 2; ++hh)
; #pragma unroll
;         for (int r = 0; r < 4; ++r)
; #pragma unroll
;             for (int jn = 0; jn < 4; ++jn) *(LAS unsigned*)(T + (256 * hh + 4 * lane + jn) * 128 + phys * 16 + r * 4) = cvt_pk_bf16(v[hh][2 * r][jn], v[hh][2 * r + 1][jn]);
;     __syncthreads();
;     const int kt = k0 >> 6, nkt = K >> 6;
; #pragma unroll
;     for (int it = 0; it < 8; ++it) { const int n = 64 * w + 8 * it + (lane >> 3), c = lane & 7;
;         const u32x4 o = *(const LAS u32x4*)(T + n * 128 + ((c ^ ((n >> 2) & 7)) << 4));
;         const int ng = n0 + n; const int d = map == 0 ? ng : (ng / 128) * 256 + (ng % 128) + (map == 2 ? 128 : 0);
;         if (d < rows_cap) *(u32x4*)(WT + ((size_t)(d >> 8) * nkt + kt) * 16384 + (d & 255) * 64 + 8 * c) = o; }
;     __syncthreads();
.LBB0_902:
	s_or_b64 exec, exec, s[2:3]
	v_xor_b32_e32 v68, s13, v67
	s_waitcnt vmcnt(0)
	v_cvt_pk_bf16_f32 v2, v2, v6
	v_lshl_add_u32 v68, v68, 4, v72
	v_cvt_pk_bf16_f32 v6, v3, v7
	v_cvt_pk_bf16_f32 v74, v4, v8
	v_cvt_pk_bf16_f32 v78, v5, v9
	v_cvt_pk_bf16_f32 v3, v14, v10
	v_cvt_pk_bf16_f32 v4, v22, v18
	v_cvt_pk_bf16_f32 v5, v30, v26
	ds_write_b128 v68, v[2:5]
	v_cvt_pk_bf16_f32 v2, v34, v38
	v_cvt_pk_bf16_f32 v3, v46, v42
	v_cvt_pk_bf16_f32 v4, v54, v50
	v_cvt_pk_bf16_f32 v5, v62, v58
	s_and_b32 s2, s9, 0xffffffc0
	ds_write_b128 v68, v[2:5] offset:32768
	v_or_b32_e32 v4, s2, v70
	s_sub_i32 s2, s2, s12
	v_cvt_pk_bf16_f32 v7, v15, v11
	v_cvt_pk_bf16_f32 v8, v23, v19
	v_cvt_pk_bf16_f32 v9, v31, v27
	s_add_i32 s2, s2, s0
	ds_write_b128 v68, v[6:9] offset:128
	v_cvt_pk_bf16_f32 v6, v35, v39
	v_cvt_pk_bf16_f32 v7, v47, v43
	v_cvt_pk_bf16_f32 v8, v55, v51
	v_cvt_pk_bf16_f32 v9, v63, v59
	v_add_u32_e32 v5, s2, v70
	v_cvt_pk_bf16_f32 v75, v16, v12
	v_cvt_pk_bf16_f32 v79, v17, v13
	v_cvt_pk_bf16_f32 v76, v24, v20
	v_cvt_pk_bf16_f32 v80, v25, v21
	v_cvt_pk_bf16_f32 v77, v32, v28
	v_cvt_pk_bf16_f32 v81, v33, v29
	v_cvt_pk_bf16_f32 v10, v36, v40
	v_cvt_pk_bf16_f32 v14, v37, v41
	v_cvt_pk_bf16_f32 v11, v48, v44
	v_cvt_pk_bf16_f32 v15, v49, v45
	v_cvt_pk_bf16_f32 v12, v56, v52
	v_cvt_pk_bf16_f32 v16, v57, v53
	ds_write_b128 v68, v[6:9] offset:32896
	v_cvt_pk_bf16_f32 v13, v64, v60
	v_cvt_pk_bf16_f32 v17, v65, v61
	s_ashr_i32 s9, s8, 31
	v_cmp_gt_i32_e32 vcc, s72, v5
	v_lshlrev_b32_e32 v6, 7, v4
	v_lshlrev_b32_e32 v2, 1, v66
	ds_write_b128 v68, v[74:77] offset:256
	ds_write_b128 v68, v[78:81] offset:384
	ds_write_b128 v68, v[10:13] offset:33024
	ds_write_b128 v68, v[14:17] offset:33152
	s_waitcnt lgkmcnt(0)
	s_barrier
	s_and_saveexec_b64 s[2:3], vcc
	s_cbranch_execz .LBB0_904
	v_ashrrev_i32_e32 v12, 8, v5
	v_add_u32_e32 v3, v71, v6
	v_ashrrev_i32_e32 v13, 31, v12
	ds_read_b128 v[8:11], v3
	v_lshlrev_b64 v[12:13], 20, v[12:13]
	s_lshl_b64 s[10:11], s[8:9], 15
	v_lshl_add_u64 v[12:13], s[6:7], 0, v[12:13]
	v_lshl_add_u64 v[12:13], v[12:13], 0, s[10:11]
	v_and_b32_e32 v14, 0x6380, v6
	v_mov_b32_e32 v15, v0
	v_lshl_add_u64 v[12:13], v[12:13], 0, v[14:15]
	v_mov_b32_e32 v3, v0
	v_lshl_add_u64 v[12:13], v[12:13], 0, v[2:3]
	s_waitcnt lgkmcnt(0)
	global_store_dwordx4 v[12:13], v[8:11], off nt
.LBB0_904:
	s_or_b64 exec, exec, s[2:3]
	v_add_u32_e32 v3, 8, v5
	v_cmp_gt_i32_e32 vcc, s72, v3
	s_and_saveexec_b64 s[2:3], vcc
	s_cbranch_execz .LBB0_906
	v_or_b32_e32 v7, 8, v4
	v_lshlrev_b32_e32 v14, 7, v7
	v_lshrrev_b32_e32 v7, 2, v7
	v_xor_b32_e32 v7, v7, v194
	v_lshlrev_b32_e32 v7, 4, v7
	v_and_b32_e32 v7, 0x70, v7
	v_ashrrev_i32_e32 v12, 8, v3
	v_add3_u32 v7, 0, v14, v7
	v_ashrrev_i32_e32 v13, 31, v12
	ds_read_b128 v[8:11], v7
	v_lshlrev_b64 v[12:13], 20, v[12:13]
	s_lshl_b64 s[10:11], s[8:9], 15
	v_lshl_add_u64 v[12:13], s[6:7], 0, v[12:13]
	v_lshl_add_u64 v[12:13], v[12:13], 0, s[10:11]
	v_and_b32_e32 v14, 0x6780, v14
	v_mov_b32_e32 v15, v0
	v_lshl_add_u64 v[12:13], v[12:13], 0, v[14:15]
	v_mov_b32_e32 v3, v0
	v_lshl_add_u64 v[12:13], v[12:13], 0, v[2:3]
	s_waitcnt lgkmcnt(0)
	global_store_dwordx4 v[12:13], v[8:11], off nt
.LBB0_906:
	s_or_b64 exec, exec, s[2:3]
	v_add_u32_e32 v3, 16, v5
	v_cmp_gt_i32_e32 vcc, s72, v3
	s_and_saveexec_b64 s[2:3], vcc
	s_cbranch_execz .LBB0_908
	v_or_b32_e32 v7, 16, v4
	v_lshlrev_b32_e32 v14, 7, v7
	v_lshrrev_b32_e32 v7, 2, v7
	v_xor_b32_e32 v7, v7, v194
	v_lshlrev_b32_e32 v7, 4, v7
	v_and_b32_e32 v7, 0x70, v7
	v_ashrrev_i32_e32 v12, 8, v3
	v_add3_u32 v7, 0, v14, v7
	v_ashrrev_i32_e32 v13, 31, v12
	ds_read_b128 v[8:11], v7
	v_lshlrev_b64 v[12:13], 20, v[12:13]
	s_lshl_b64 s[10:11], s[8:9], 15
	v_lshl_add_u64 v[12:13], s[6:7], 0, v[12:13]
	v_lshl_add_u64 v[12:13], v[12:13], 0, s[10:11]
	v_and_b32_e32 v14, 0x6b80, v14
	v_mov_b32_e32 v15, v0
	v_lshl_add_u64 v[12:13], v[12:13], 0, v[14:15]
	v_mov_b32_e32 v3, v0
	v_lshl_add_u64 v[12:13], v[12:13], 0, v[2:3]
	s_waitcnt lgkmcnt(0)
	global_store_dwordx4 v[12:13], v[8:11], off nt
; #define LAS __attribute__((address_space(3)))
; __device__ __forceinline__ void cvt_tile(const float* W, int ldw, int nvalid, int k0, int n0, bf16_t* WT, int K, int map, int rows_cap, LAS unsigned char* T, int tid, const float* gvec) {
;     ...
;     for (int it = 0; it < 8; ++it) { const int n = 64 * w + 8 * it + (lane >> 3), c = lane & 7;
;         const u32x4 o = *(const LAS u32x4*)(T + n * 128 + ((c ^ ((n >> 2) & 7)) << 4));
;         const int ng = n0 + n; const int d = map == 0 ? ng : (ng / 128) * 256 + (ng % 128) + (map == 2 ? 128 : 0);
;         if (d < rows_cap) *(u32x4*)(WT + ((size_t)(d >> 8) * nkt + kt) * 16384 + (d & 255) * 64 + 8 * c) = o; }
;     __syncthreads();
.LBB0_908:
	s_or_b64 exec, exec, s[2:3]
	v_add_u32_e32 v3, 24, v5
	v_cmp_gt_i32_e32 vcc, s72, v3
	s_and_saveexec_b64 s[2:3], vcc
	s_cbranch_execz .LBB0_910
	v_or_b32_e32 v7, 24, v4
	v_lshlrev_b32_e32 v14, 7, v7
	v_lshrrev_b32_e32 v7, 2, v7
	v_xor_b32_e32 v7, v7, v194
	v_lshlrev_b32_e32 v7, 4, v7
	v_and_b32_e32 v7, 0x70, v7
	v_ashrrev_i32_e32 v12, 8, v3
	v_add3_u32 v7, 0, v14, v7
	v_ashrrev_i32_e32 v13, 31, v12
	ds_read_b128 v[8:11], v7
	v_lshlrev_b64 v[12:13], 20, v[12:13]
	s_lshl_b64 s[10:11], s[8:9], 15
	v_lshl_add_u64 v[12:13], s[6:7], 0, v[12:13]
	v_lshl_add_u64 v[12:13], v[12:13], 0, s[10:11]
	v_and_b32_e32 v14, 0x6f80, v14
	v_mov_b32_e32 v15, v0
	v_lshl_add_u64 v[12:13], v[12:13], 0, v[14:15]
	v_mov_b32_e32 v3, v0
	v_lshl_add_u64 v[12:13], v[12:13], 0, v[2:3]
	s_waitcnt lgkmcnt(0)
	global_store_dwordx4 v[12:13], v[8:11], off nt
.LBB0_910:
	s_or_b64 exec, exec, s[2:3]
	v_add_u32_e32 v3, 32, v5
	v_cmp_gt_i32_e32 vcc, s72, v3
	s_and_saveexec_b64 s[2:3], vcc
	s_cbranch_execz .LBB0_912
	v_or_b32_e32 v7, 0x1000, v6
	v_ashrrev_i32_e32 v12, 8, v3
	v_add_u32_e32 v7, v71, v7
	v_ashrrev_i32_e32 v13, 31, v12
	ds_read_b128 v[8:11], v7
	v_lshlrev_b64 v[12:13], 20, v[12:13]
	s_lshl_b64 s[10:11], s[8:9], 15
	v_lshl_add_u64 v[12:13], s[6:7], 0, v[12:13]
	v_lshl_add_u64 v[12:13], v[12:13], 0, s[10:11]
	v_bitop3_b32 v6, v6, s74, v216 bitop3:0xc8
	v_mov_b32_e32 v7, v0
	v_lshl_add_u64 v[6:7], v[12:13], 0, v[6:7]
	v_mov_b32_e32 v3, v0
	v_lshl_add_u64 v[6:7], v[6:7], 0, v[2:3]
	s_waitcnt lgkmcnt(0)
	global_store_dwordx4 v[6:7], v[8:11], off nt
.LBB0_912:
	s_or_b64 exec, exec, s[2:3]
	v_add_u32_e32 v3, 40, v5
	v_cmp_gt_i32_e32 vcc, s72, v3
	s_and_saveexec_b64 s[2:3], vcc
	s_cbranch_execz .LBB0_914
	v_or_b32_e32 v6, 40, v4
	v_lshlrev_b32_e32 v12, 7, v6
	v_lshrrev_b32_e32 v6, 2, v6
	v_xor_b32_e32 v6, v6, v194
	v_lshlrev_b32_e32 v6, 4, v6
	v_and_b32_e32 v6, 0x70, v6
	v_ashrrev_i32_e32 v10, 8, v3
	v_add3_u32 v6, 0, v12, v6
	v_ashrrev_i32_e32 v11, 31, v10
	ds_read_b128 v[6:9], v6
	v_lshlrev_b64 v[10:11], 20, v[10:11]
	s_lshl_b64 s[10:11], s[8:9], 15
	v_lshl_add_u64 v[10:11], s[6:7], 0, v[10:11]
	v_lshl_add_u64 v[10:11], v[10:11], 0, s[10:11]
	v_and_b32_e32 v12, 0x7780, v12
	v_mov_b32_e32 v13, v0
	v_lshl_add_u64 v[10:11], v[10:11], 0, v[12:13]
	v_mov_b32_e32 v3, v0
	v_lshl_add_u64 v[10:11], v[10:11], 0, v[2:3]
	s_waitcnt lgkmcnt(0)
	global_store_dwordx4 v[10:11], v[6:9], off nt
.LBB0_914:
	s_or_b64 exec, exec, s[2:3]
	v_add_u32_e32 v3, 48, v5
	v_cmp_gt_i32_e32 vcc, s72, v3
	s_and_saveexec_b64 s[2:3], vcc
	s_cbranch_execz .LBB0_916
	v_or_b32_e32 v6, 48, v4
	v_lshlrev_b32_e32 v12, 7, v6
	v_lshrrev_b32_e32 v6, 2, v6
	v_xor_b32_e32 v6, v6, v194
	v_lshlrev_b32_e32 v6, 4, v6
	v_and_b32_e32 v6, 0x70, v6
	v_ashrrev_i32_e32 v10, 8, v3
	v_add3_u32 v6, 0, v12, v6
	v_ashrrev_i32_e32 v11, 31, v10
	ds_read_b128 v[6:9], v6
	v_lshlrev_b64 v[10:11], 20, v[10:11]
	s_lshl_b64 s[10:11], s[8:9], 15
	v_lshl_add_u64 v[10:11], s[6:7], 0, v[10:11]
	v_lshl_add_u64 v[10:11], v[10:11], 0, s[10:11]
	v_and_b32_e32 v12, 0x7b80, v12
	v_mov_b32_e32 v13, v0
	v_lshl_add_u64 v[10:11], v[10:11], 0, v[12:13]
	v_mov_b32_e32 v3, v0
	v_lshl_add_u64 v[10:11], v[10:11], 0, v[2:3]
	s_waitcnt lgkmcnt(0)
	global_store_dwordx4 v[10:11], v[6:9], off nt
.LBB0_916:
	s_or_b64 exec, exec, s[2:3]
	v_add_u32_e32 v3, 56, v5
	v_cmp_gt_i32_e32 vcc, s72, v3
	s_and_saveexec_b64 s[2:3], vcc
	s_cbranch_execz .LBB0_869
	v_or_b32_e32 v4, 56, v4
	v_lshlrev_b32_e32 v10, 7, v4
	v_lshrrev_b32_e32 v4, 2, v4
	v_xor_b32_e32 v4, v4, v194
	v_lshlrev_b32_e32 v4, 4, v4
	v_and_b32_e32 v4, 0x70, v4
	v_ashrrev_i32_e32 v8, 8, v3
	v_add3_u32 v4, 0, v10, v4
	v_ashrrev_i32_e32 v9, 31, v8
	ds_read_b128 v[4:7], v4
	v_lshlrev_b64 v[8:9], 20, v[8:9]
	s_lshl_b64 s[8:9], s[8:9], 15
	v_lshl_add_u64 v[8:9], s[6:7], 0, v[8:9]
	v_lshl_add_u64 v[8:9], v[8:9], 0, s[8:9]
	v_and_b32_e32 v10, 0x7f80, v10
	v_mov_b32_e32 v11, v0
	v_lshl_add_u64 v[8:9], v[8:9], 0, v[10:11]
	v_mov_b32_e32 v3, v0
	v_lshl_add_u64 v[2:3], v[8:9], 0, v[2:3]
	s_waitcnt lgkmcnt(0)
	global_store_dwordx4 v[2:3], v[4:7], off nt
	s_branch .LBB0_869

; #define LAS __attribute__((address_space(3)))
; __device__ __forceinline__ unsigned cvt_pk_bf16(float lo, float hi) { f32x2 v = {lo, hi}; bf16x2_t b = __builtin_convertvector(v, bf16x2_t); return __builtin_bit_cast(unsigned, b); }
; __device__ __forceinline__ void cvt_tile(const float* W, int ldw, int nvalid, int k0, int n0, bf16_t* WT, int K, int map, int rows_cap, LAS unsigned char* T, int tid, const float* gvec) {
;     ...
;     const int phys = w ^ (lane & 7);
; #pragma unroll
;     for (int hh = 0; hh < 2; ++hh)
; #pragma unroll
;         for (int r = 0; r < 4; ++r)
; #pragma unroll
;             for (int jn = 0; jn < 4; ++jn) *(LAS unsigned*)(T + (256 * hh + 4 * lane + jn) * 128 + phys * 16 + r * 4) = cvt_pk_bf16(v[hh][2 * r][jn], v[hh][2 * r + 1][jn]);
;     __syncthreads();
;     const int kt = k0 >> 6, nkt = K >> 6;
; #pragma unroll
;     for (int it = 0; it < 8; ++it) { const int n = 64 * w + 8 * it + (lane >> 3), c = lane & 7;
;         const u32x4 o = *(const LAS u32x4*)(T + n * 128 + ((c ^ ((n >> 2) & 7)) << 4));
;         const int ng = n0 + n; const int d = map == 0 ? ng : (ng / 128) * 256 + (ng % 128) + (map == 2 ? 128 : 0);
;         if (d < rows_cap) *(u32x4*)(WT + ((size_t)(d >> 8) * nkt + kt) * 16384 + (d & 255) * 64 + 8 * c) = o; }
;     __syncthreads();
.LBB0_957:
	v_xor_b32_e32 v1, s18, v79
	s_waitcnt vmcnt(0)
	v_cvt_pk_bf16_f32 v2, v4, v8
	v_lshl_add_u32 v1, v1, 4, v75
	v_cvt_pk_bf16_f32 v8, v5, v9
	v_cvt_pk_bf16_f32 v82, v6, v10
	v_cvt_pk_bf16_f32 v86, v7, v11
	v_cvt_pk_bf16_f32 v3, v12, v16
	v_cvt_pk_bf16_f32 v9, v13, v17
	v_cvt_pk_bf16_f32 v4, v20, v28
	v_cvt_pk_bf16_f32 v10, v21, v29
	v_cvt_pk_bf16_f32 v5, v24, v32
	v_cvt_pk_bf16_f32 v11, v25, v33
	v_cvt_pk_bf16_f32 v83, v14, v18
	v_cvt_pk_bf16_f32 v87, v15, v19
	v_cvt_pk_bf16_f32 v84, v22, v30
	v_cvt_pk_bf16_f32 v88, v23, v31
	ds_write_b128 v1, v[2:5]
	ds_write_b128 v1, v[8:11] offset:128
	v_cvt_pk_bf16_f32 v85, v26, v34
	v_cvt_pk_bf16_f32 v89, v27, v35
	v_cvt_pk_bf16_f32 v2, v36, v40
	v_cvt_pk_bf16_f32 v6, v37, v41
	v_cvt_pk_bf16_f32 v10, v38, v42
	v_cvt_pk_bf16_f32 v14, v39, v43
	v_cvt_pk_bf16_f32 v3, v44, v48
	v_cvt_pk_bf16_f32 v7, v45, v49
	v_cvt_pk_bf16_f32 v11, v46, v50
	v_cvt_pk_bf16_f32 v15, v47, v51
	v_cvt_pk_bf16_f32 v4, v52, v60
	v_cvt_pk_bf16_f32 v8, v53, v61
	v_cvt_pk_bf16_f32 v12, v54, v62
	v_cvt_pk_bf16_f32 v16, v55, v63
	v_cvt_pk_bf16_f32 v5, v56, v64
	v_cvt_pk_bf16_f32 v9, v57, v65
	v_cvt_pk_bf16_f32 v13, v58, v66
	v_cvt_pk_bf16_f32 v17, v59, v67
	s_and_b32 s2, s15, 0xffffffc0
	s_mul_i32 s3, s14, 0x1a00
	ds_write_b128 v1, v[82:85] offset:256
	ds_write_b128 v1, v[86:89] offset:384
	ds_write_b128 v1, v[2:5] offset:32768
	ds_write_b128 v1, v[6:9] offset:32896
	ds_write_b128 v1, v[10:13] offset:33024
	ds_write_b128 v1, v[14:17] offset:33152
	v_or_b32_e32 v1, s2, v80
	s_sub_i32 s2, s2, s3
	s_add_i32 s2, s2, s0
	v_add_u32_e32 v4, s2, v80
	s_ashr_i32 s15, s14, 31
	v_cmp_gt_i32_e32 vcc, s22, v4
	v_lshlrev_b32_e32 v5, 7, v1
	v_lshlrev_b32_e32 v2, 1, v68
	s_waitcnt lgkmcnt(0)
	s_barrier
	s_and_saveexec_b64 s[2:3], vcc
	s_cbranch_execz .LBB0_959
	v_ashrrev_i32_e32 v10, 8, v4
	v_add_u32_e32 v3, v74, v5
	v_ashrrev_i32_e32 v11, 31, v10
	ds_read_b128 v[6:9], v3
	v_lshlrev_b64 v[10:11], 20, v[10:11]
	s_lshl_b64 s[16:17], s[14:15], 15
	v_lshl_add_u64 v[10:11], s[6:7], 0, v[10:11]
	v_lshl_add_u64 v[10:11], v[10:11], 0, s[16:17]
	v_and_b32_e32 v12, 0x6380, v5
	v_mov_b32_e32 v13, v0
	v_lshl_add_u64 v[10:11], v[10:11], 0, v[12:13]
	v_mov_b32_e32 v3, v0
	v_lshl_add_u64 v[10:11], v[10:11], 0, v[2:3]
	s_waitcnt lgkmcnt(0)
	global_store_dwordx4 v[10:11], v[6:9], off nt
.LBB0_959:
	s_or_b64 exec, exec, s[2:3]
	v_add_u32_e32 v3, 8, v4
	v_cmp_gt_i32_e32 vcc, s22, v3
	s_and_saveexec_b64 s[2:3], vcc
	s_cbranch_execz .LBB0_961
	v_or_b32_e32 v6, 8, v1
	v_lshlrev_b32_e32 v12, 7, v6
	v_lshrrev_b32_e32 v6, 2, v6
	v_xor_b32_e32 v6, v6, v194
	v_lshlrev_b32_e32 v6, 4, v6
	v_and_b32_e32 v6, 0x70, v6
	v_ashrrev_i32_e32 v10, 8, v3
	v_add3_u32 v6, 0, v12, v6
	v_ashrrev_i32_e32 v11, 31, v10
	ds_read_b128 v[6:9], v6
	v_lshlrev_b64 v[10:11], 20, v[10:11]
	s_lshl_b64 s[16:17], s[14:15], 15
	v_lshl_add_u64 v[10:11], s[6:7], 0, v[10:11]
	v_lshl_add_u64 v[10:11], v[10:11], 0, s[16:17]
	v_and_b32_e32 v12, 0x6780, v12
	v_mov_b32_e32 v13, v0
	v_lshl_add_u64 v[10:11], v[10:11], 0, v[12:13]
	v_mov_b32_e32 v3, v0
	v_lshl_add_u64 v[10:11], v[10:11], 0, v[2:3]
	s_waitcnt lgkmcnt(0)
	global_store_dwordx4 v[10:11], v[6:9], off nt
.LBB0_961:
	s_or_b64 exec, exec, s[2:3]
	v_add_u32_e32 v3, 16, v4
	v_cmp_gt_i32_e32 vcc, s22, v3
	s_and_saveexec_b64 s[2:3], vcc
	s_cbranch_execz .LBB0_963
	v_or_b32_e32 v6, 16, v1
	v_lshlrev_b32_e32 v12, 7, v6
	v_lshrrev_b32_e32 v6, 2, v6
	v_xor_b32_e32 v6, v6, v194
	v_lshlrev_b32_e32 v6, 4, v6
	v_and_b32_e32 v6, 0x70, v6
	v_ashrrev_i32_e32 v10, 8, v3
	v_add3_u32 v6, 0, v12, v6
	v_ashrrev_i32_e32 v11, 31, v10
	ds_read_b128 v[6:9], v6
	v_lshlrev_b64 v[10:11], 20, v[10:11]
	s_lshl_b64 s[16:17], s[14:15], 15
	v_lshl_add_u64 v[10:11], s[6:7], 0, v[10:11]
	v_lshl_add_u64 v[10:11], v[10:11], 0, s[16:17]
	v_and_b32_e32 v12, 0x6b80, v12
	v_mov_b32_e32 v13, v0
	v_lshl_add_u64 v[10:11], v[10:11], 0, v[12:13]
	v_mov_b32_e32 v3, v0
	v_lshl_add_u64 v[10:11], v[10:11], 0, v[2:3]
	s_waitcnt lgkmcnt(0)
	global_store_dwordx4 v[10:11], v[6:9], off nt
; #define LAS __attribute__((address_space(3)))
; __device__ __forceinline__ void cvt_tile(const float* W, int ldw, int nvalid, int k0, int n0, bf16_t* WT, int K, int map, int rows_cap, LAS unsigned char* T, int tid, const float* gvec) {
;     ...
;     for (int it = 0; it < 8; ++it) { const int n = 64 * w + 8 * it + (lane >> 3), c = lane & 7;
;         const u32x4 o = *(const LAS u32x4*)(T + n * 128 + ((c ^ ((n >> 2) & 7)) << 4));
;         const int ng = n0 + n; const int d = map == 0 ? ng : (ng / 128) * 256 + (ng % 128) + (map == 2 ? 128 : 0);
;         if (d < rows_cap) *(u32x4*)(WT + ((size_t)(d >> 8) * nkt + kt) * 16384 + (d & 255) * 64 + 8 * c) = o; }
;     __syncthreads();
.LBB0_963:
	s_or_b64 exec, exec, s[2:3]
	v_add_u32_e32 v3, 24, v4
	v_cmp_gt_i32_e32 vcc, s22, v3
	s_and_saveexec_b64 s[2:3], vcc
	s_cbranch_execz .LBB0_965
	v_or_b32_e32 v6, 24, v1
	v_lshlrev_b32_e32 v12, 7, v6
	v_lshrrev_b32_e32 v6, 2, v6
	v_xor_b32_e32 v6, v6, v194
	v_lshlrev_b32_e32 v6, 4, v6
	v_and_b32_e32 v6, 0x70, v6
	v_ashrrev_i32_e32 v10, 8, v3
	v_add3_u32 v6, 0, v12, v6
	v_ashrrev_i32_e32 v11, 31, v10
	ds_read_b128 v[6:9], v6
	v_lshlrev_b64 v[10:11], 20, v[10:11]
	s_lshl_b64 s[16:17], s[14:15], 15
	v_lshl_add_u64 v[10:11], s[6:7], 0, v[10:11]
	v_lshl_add_u64 v[10:11], v[10:11], 0, s[16:17]
	v_and_b32_e32 v12, 0x6f80, v12
	v_mov_b32_e32 v13, v0
	v_lshl_add_u64 v[10:11], v[10:11], 0, v[12:13]
	v_mov_b32_e32 v3, v0
	v_lshl_add_u64 v[10:11], v[10:11], 0, v[2:3]
	s_waitcnt lgkmcnt(0)
	global_store_dwordx4 v[10:11], v[6:9], off nt
.LBB0_965:
	s_or_b64 exec, exec, s[2:3]
	v_add_u32_e32 v3, 32, v4
	v_cmp_gt_i32_e32 vcc, s22, v3
	s_and_saveexec_b64 s[2:3], vcc
	s_cbranch_execz .LBB0_967
	v_or_b32_e32 v6, 0x1000, v5
	v_ashrrev_i32_e32 v10, 8, v3
	v_add_u32_e32 v6, v74, v6
	v_ashrrev_i32_e32 v11, 31, v10
	ds_read_b128 v[6:9], v6
	v_lshlrev_b64 v[10:11], 20, v[10:11]
	s_lshl_b64 s[16:17], s[14:15], 15
	v_lshl_add_u64 v[10:11], s[6:7], 0, v[10:11]
	v_lshl_add_u64 v[10:11], v[10:11], 0, s[16:17]
	v_bitop3_b32 v12, v5, s74, v216 bitop3:0xc8
	v_mov_b32_e32 v13, v0
	v_lshl_add_u64 v[10:11], v[10:11], 0, v[12:13]
	v_mov_b32_e32 v3, v0
	v_lshl_add_u64 v[10:11], v[10:11], 0, v[2:3]
	s_waitcnt lgkmcnt(0)
	global_store_dwordx4 v[10:11], v[6:9], off nt
.LBB0_967:
	s_or_b64 exec, exec, s[2:3]
	v_add_u32_e32 v3, 40, v4
	v_cmp_gt_i32_e32 vcc, s22, v3
	s_and_saveexec_b64 s[2:3], vcc
	s_cbranch_execz .LBB0_969
	v_or_b32_e32 v5, 40, v1
	v_lshlrev_b32_e32 v12, 7, v5
	v_lshrrev_b32_e32 v5, 2, v5
	v_xor_b32_e32 v5, v5, v194
	v_lshlrev_b32_e32 v5, 4, v5
	v_and_b32_e32 v5, 0x70, v5
	v_ashrrev_i32_e32 v10, 8, v3
	v_add3_u32 v5, 0, v12, v5
	v_ashrrev_i32_e32 v11, 31, v10
	ds_read_b128 v[6:9], v5
	v_lshlrev_b64 v[10:11], 20, v[10:11]
	s_lshl_b64 s[16:17], s[14:15], 15
	v_lshl_add_u64 v[10:11], s[6:7], 0, v[10:11]
	v_lshl_add_u64 v[10:11], v[10:11], 0, s[16:17]
	v_and_b32_e32 v12, 0x7780, v12
	v_mov_b32_e32 v13, v0
	v_lshl_add_u64 v[10:11], v[10:11], 0, v[12:13]
	v_mov_b32_e32 v3, v0
	v_lshl_add_u64 v[10:11], v[10:11], 0, v[2:3]
	s_waitcnt lgkmcnt(0)
	global_store_dwordx4 v[10:11], v[6:9], off nt
.LBB0_969:
	s_or_b64 exec, exec, s[2:3]
	v_add_u32_e32 v3, 48, v4
	v_cmp_gt_i32_e32 vcc, s22, v3
	s_and_saveexec_b64 s[2:3], vcc
	s_cbranch_execz .LBB0_971
	v_or_b32_e32 v5, 48, v1
	v_lshlrev_b32_e32 v12, 7, v5
	v_lshrrev_b32_e32 v5, 2, v5
	v_xor_b32_e32 v5, v5, v194
	v_lshlrev_b32_e32 v5, 4, v5
	v_and_b32_e32 v5, 0x70, v5
	v_ashrrev_i32_e32 v10, 8, v3
	v_add3_u32 v5, 0, v12, v5
	v_ashrrev_i32_e32 v11, 31, v10
	ds_read_b128 v[6:9], v5
	v_lshlrev_b64 v[10:11], 20, v[10:11]
	s_lshl_b64 s[16:17], s[14:15], 15
	v_lshl_add_u64 v[10:11], s[6:7], 0, v[10:11]
	v_lshl_add_u64 v[10:11], v[10:11], 0, s[16:17]
	v_and_b32_e32 v12, 0x7b80, v12
	v_mov_b32_e32 v13, v0
	v_lshl_add_u64 v[10:11], v[10:11], 0, v[12:13]
	v_mov_b32_e32 v3, v0
	v_lshl_add_u64 v[10:11], v[10:11], 0, v[2:3]
	s_waitcnt lgkmcnt(0)
	global_store_dwordx4 v[10:11], v[6:9], off nt
.LBB0_971:
	s_or_b64 exec, exec, s[2:3]
	v_add_u32_e32 v3, 56, v4
	v_cmp_gt_i32_e32 vcc, s22, v3
	s_and_saveexec_b64 s[2:3], vcc
	s_cbranch_execz .LBB0_922
	v_or_b32_e32 v1, 56, v1
	v_lshlrev_b32_e32 v10, 7, v1
	v_lshrrev_b32_e32 v1, 2, v1
	v_xor_b32_e32 v1, v1, v194
	v_lshlrev_b32_e32 v1, 4, v1
	v_and_b32_e32 v1, 0x70, v1
	v_ashrrev_i32_e32 v8, 8, v3
	v_add3_u32 v1, 0, v10, v1
	v_ashrrev_i32_e32 v9, 31, v8
	ds_read_b128 v[4:7], v1
	v_lshlrev_b64 v[8:9], 20, v[8:9]
	s_lshl_b64 s[14:15], s[14:15], 15
	v_lshl_add_u64 v[8:9], s[6:7], 0, v[8:9]
	v_lshl_add_u64 v[8:9], v[8:9], 0, s[14:15]
	v_and_b32_e32 v10, 0x7f80, v10
	v_mov_b32_e32 v11, v0
	v_lshl_add_u64 v[8:9], v[8:9], 0, v[10:11]
	v_mov_b32_e32 v3, v0
	v_lshl_add_u64 v[2:3], v[8:9], 0, v[2:3]
	s_waitcnt lgkmcnt(0)
	global_store_dwordx4 v[2:3], v[4:7], off nt
	s_branch .LBB0_922

; #define LAS __attribute__((address_space(3)))
; __device__ __forceinline__ unsigned cvt_pk_bf16(float lo, float hi) { f32x2 v = {lo, hi}; bf16x2_t b = __builtin_convertvector(v, bf16x2_t); return __builtin_bit_cast(unsigned, b); }
; __device__ __forceinline__ void cvt_tile(const float* W, int ldw, int nvalid, int k0, int n0, bf16_t* WT, int K, int map, int rows_cap, LAS unsigned char* T, int tid, const float* gvec) {
;     ...
;     const int phys = w ^ (lane & 7);
; #pragma unroll
;     for (int hh = 0; hh < 2; ++hh)
; #pragma unroll
;         for (int r = 0; r < 4; ++r)
; #pragma unroll
;             for (int jn = 0; jn < 4; ++jn) *(LAS unsigned*)(T + (256 * hh + 4 * lane + jn) * 128 + phys * 16 + r * 4) = cvt_pk_bf16(v[hh][2 * r][jn], v[hh][2 * r + 1][jn]);
;     __syncthreads();
;     const int kt = k0 >> 6, nkt = K >> 6;
; #pragma unroll
;     for (int it = 0; it < 8; ++it) { const int n = 64 * w + 8 * it + (lane >> 3), c = lane & 7;
;         const u32x4 o = *(const LAS u32x4*)(T + n * 128 + ((c ^ ((n >> 2) & 7)) << 4));
;         const int ng = n0 + n; const int d = map == 0 ? ng : (ng / 128) * 256 + (ng % 128) + (map == 2 ? 128 : 0);
;         if (d < rows_cap) *(u32x4*)(WT + ((size_t)(d >> 8) * nkt + kt) * 16384 + (d & 255) * 64 + 8 * c) = o; }
;     __syncthreads();
.LBB0_1008:
	s_or_b64 exec, exec, s[2:3]
	v_xor_b32_e32 v1, s13, v79
	s_waitcnt vmcnt(0)
	v_cvt_pk_bf16_f32 v2, v2, v6
	v_lshl_add_u32 v1, v1, 4, v82
	v_cvt_pk_bf16_f32 v6, v3, v7
	v_cvt_pk_bf16_f32 v70, v4, v8
	v_cvt_pk_bf16_f32 v74, v5, v9
	v_cvt_pk_bf16_f32 v3, v14, v10
	v_cvt_pk_bf16_f32 v7, v15, v11
	v_cvt_pk_bf16_f32 v4, v22, v18
	v_cvt_pk_bf16_f32 v8, v23, v19
	v_cvt_pk_bf16_f32 v5, v30, v26
	v_cvt_pk_bf16_f32 v9, v31, v27
	v_cvt_pk_bf16_f32 v71, v16, v12
	v_cvt_pk_bf16_f32 v75, v17, v13
	v_cvt_pk_bf16_f32 v72, v24, v20
	v_cvt_pk_bf16_f32 v76, v25, v21
	ds_write_b128 v1, v[2:5]
	ds_write_b128 v1, v[6:9] offset:128
	v_cvt_pk_bf16_f32 v73, v32, v28
	v_cvt_pk_bf16_f32 v77, v33, v29
	v_cvt_pk_bf16_f32 v2, v34, v38
	v_cvt_pk_bf16_f32 v6, v35, v39
	v_cvt_pk_bf16_f32 v10, v36, v40
	v_cvt_pk_bf16_f32 v14, v37, v41
	v_cvt_pk_bf16_f32 v3, v46, v42
	v_cvt_pk_bf16_f32 v7, v47, v43
	v_cvt_pk_bf16_f32 v11, v48, v44
	v_cvt_pk_bf16_f32 v15, v49, v45
	v_cvt_pk_bf16_f32 v4, v54, v50
	v_cvt_pk_bf16_f32 v8, v55, v51
	v_cvt_pk_bf16_f32 v12, v56, v52
	v_cvt_pk_bf16_f32 v16, v57, v53
	v_cvt_pk_bf16_f32 v5, v62, v58
	v_cvt_pk_bf16_f32 v9, v63, v59
	v_cvt_pk_bf16_f32 v13, v64, v60
	v_cvt_pk_bf16_f32 v17, v65, v61
	s_and_b32 s2, s9, 0xffffffc0
	ds_write_b128 v1, v[70:73] offset:256
	ds_write_b128 v1, v[74:77] offset:384
	ds_write_b128 v1, v[2:5] offset:32768
	ds_write_b128 v1, v[6:9] offset:32896
	ds_write_b128 v1, v[10:13] offset:33024
	ds_write_b128 v1, v[14:17] offset:33152
	v_or_b32_e32 v1, s2, v80
	s_sub_i32 s2, s2, s12
	s_add_i32 s2, s2, s0
	v_add_u32_e32 v2, s2, v80
	s_ashr_i32 s9, s8, 31
	v_cmp_gt_i32_e32 vcc, s72, v2
	v_lshlrev_b32_e32 v3, 7, v1
	s_waitcnt lgkmcnt(0)
	s_barrier
	s_and_saveexec_b64 s[2:3], vcc
	s_cbranch_execz .LBB0_1010
	v_ashrrev_i32_e32 v8, 8, v2
	v_add_u32_e32 v4, v81, v3
	v_ashrrev_i32_e32 v9, 31, v8
	ds_read_b128 v[4:7], v4
	v_lshlrev_b64 v[8:9], 20, v[8:9]
	s_lshl_b64 s[10:11], s[8:9], 15
	v_lshl_add_u64 v[8:9], s[6:7], 0, v[8:9]
	v_lshl_add_u64 v[8:9], v[8:9], 0, s[10:11]
	v_and_b32_e32 v10, 0x6380, v3
	v_mov_b32_e32 v11, v0
	v_lshl_add_u64 v[8:9], v[8:9], 0, v[10:11]
	v_lshl_add_u64 v[8:9], v[68:69], 1, v[8:9]
	s_waitcnt lgkmcnt(0)
	global_store_dwordx4 v[8:9], v[4:7], off nt
.LBB0_1010:
	s_or_b64 exec, exec, s[2:3]
	s_nop 0
	v_add_u32_e32 v4, 8, v2
	v_cmp_gt_i32_e32 vcc, s72, v4
	s_and_saveexec_b64 s[2:3], vcc
	s_cbranch_execz .LBB0_1012
	v_or_b32_e32 v5, 8, v1
	v_lshlrev_b32_e32 v10, 7, v5
	v_lshrrev_b32_e32 v5, 2, v5
	v_xor_b32_e32 v5, v5, v194
	v_lshlrev_b32_e32 v5, 4, v5
	v_and_b32_e32 v5, 0x70, v5
	v_add3_u32 v5, 0, v10, v5
	v_ashrrev_i32_e32 v4, 8, v4
	ds_read_b128 v[6:9], v5
	v_ashrrev_i32_e32 v5, 31, v4
	v_lshlrev_b64 v[4:5], 20, v[4:5]
	s_lshl_b64 s[10:11], s[8:9], 15
	v_lshl_add_u64 v[4:5], s[6:7], 0, v[4:5]
	v_lshl_add_u64 v[4:5], v[4:5], 0, s[10:11]
	v_and_b32_e32 v10, 0x6780, v10
	v_mov_b32_e32 v11, v0
	v_lshl_add_u64 v[4:5], v[4:5], 0, v[10:11]
	v_lshl_add_u64 v[4:5], v[68:69], 1, v[4:5]
	s_waitcnt lgkmcnt(0)
	global_store_dwordx4 v[4:5], v[6:9], off nt
.LBB0_1012:
	s_or_b64 exec, exec, s[2:3]
	v_add_u32_e32 v4, 16, v2
	v_cmp_gt_i32_e32 vcc, s72, v4
	s_and_saveexec_b64 s[2:3], vcc
	s_cbranch_execz .LBB0_1014
	v_or_b32_e32 v5, 16, v1
	v_lshlrev_b32_e32 v10, 7, v5
	v_lshrrev_b32_e32 v5, 2, v5
	v_xor_b32_e32 v5, v5, v194
	v_lshlrev_b32_e32 v5, 4, v5
	v_and_b32_e32 v5, 0x70, v5
	v_add3_u32 v5, 0, v10, v5
	v_ashrrev_i32_e32 v4, 8, v4
	ds_read_b128 v[6:9], v5
	v_ashrrev_i32_e32 v5, 31, v4
	v_lshlrev_b64 v[4:5], 20, v[4:5]
	s_lshl_b64 s[10:11], s[8:9], 15
	v_lshl_add_u64 v[4:5], s[6:7], 0, v[4:5]
	v_lshl_add_u64 v[4:5], v[4:5], 0, s[10:11]
	v_and_b32_e32 v10, 0x6b80, v10
	v_mov_b32_e32 v11, v0
	v_lshl_add_u64 v[4:5], v[4:5], 0, v[10:11]
	v_lshl_add_u64 v[4:5], v[68:69], 1, v[4:5]
	s_waitcnt lgkmcnt(0)
	global_store_dwordx4 v[4:5], v[6:9], off nt
; #define LAS __attribute__((address_space(3)))
; __device__ __forceinline__ void cvt_tile(const float* W, int ldw, int nvalid, int k0, int n0, bf16_t* WT, int K, int map, int rows_cap, LAS unsigned char* T, int tid, const float* gvec) {
;     ...
;     for (int it = 0; it < 8; ++it) { const int n = 64 * w + 8 * it + (lane >> 3), c = lane & 7;
;         const u32x4 o = *(const LAS u32x4*)(T + n * 128 + ((c ^ ((n >> 2) & 7)) << 4));
;         const int ng = n0 + n; const int d = map == 0 ? ng : (ng / 128) * 256 + (ng % 128) + (map == 2 ? 128 : 0);
;         if (d < rows_cap) *(u32x4*)(WT + ((size_t)(d >> 8) * nkt + kt) * 16384 + (d & 255) * 64 + 8 * c) = o; }
;     __syncthreads();
.LBB0_1014:
	s_or_b64 exec, exec, s[2:3]
	v_add_u32_e32 v4, 24, v2
	v_cmp_gt_i32_e32 vcc, s72, v4
	s_and_saveexec_b64 s[2:3], vcc
	s_cbranch_execz .LBB0_1016
	v_or_b32_e32 v5, 24, v1
	v_lshlrev_b32_e32 v10, 7, v5
	v_lshrrev_b32_e32 v5, 2, v5
	v_xor_b32_e32 v5, v5, v194
	v_lshlrev_b32_e32 v5, 4, v5
	v_and_b32_e32 v5, 0x70, v5
	v_add3_u32 v5, 0, v10, v5
	v_ashrrev_i32_e32 v4, 8, v4
	ds_read_b128 v[6:9], v5
	v_ashrrev_i32_e32 v5, 31, v4
	v_lshlrev_b64 v[4:5], 20, v[4:5]
	s_lshl_b64 s[10:11], s[8:9], 15
	v_lshl_add_u64 v[4:5], s[6:7], 0, v[4:5]
	v_lshl_add_u64 v[4:5], v[4:5], 0, s[10:11]
	v_and_b32_e32 v10, 0x6f80, v10
	v_mov_b32_e32 v11, v0
	v_lshl_add_u64 v[4:5], v[4:5], 0, v[10:11]
	v_lshl_add_u64 v[4:5], v[68:69], 1, v[4:5]
	s_waitcnt lgkmcnt(0)
	global_store_dwordx4 v[4:5], v[6:9], off nt
.LBB0_1016:
	s_or_b64 exec, exec, s[2:3]
	v_add_u32_e32 v4, 32, v2
	v_cmp_gt_i32_e32 vcc, s72, v4
	s_and_saveexec_b64 s[2:3], vcc
	s_cbranch_execz .LBB0_1018
	v_or_b32_e32 v5, 0x1000, v3
	v_add_u32_e32 v5, v81, v5
	v_ashrrev_i32_e32 v4, 8, v4
	ds_read_b128 v[6:9], v5
	v_ashrrev_i32_e32 v5, 31, v4
	v_lshlrev_b64 v[4:5], 20, v[4:5]
	s_lshl_b64 s[10:11], s[8:9], 15
	v_lshl_add_u64 v[4:5], s[6:7], 0, v[4:5]
	v_lshl_add_u64 v[4:5], v[4:5], 0, s[10:11]
	v_bitop3_b32 v10, v3, s74, v216 bitop3:0xc8
	v_mov_b32_e32 v11, v0
	v_lshl_add_u64 v[4:5], v[4:5], 0, v[10:11]
	v_lshl_add_u64 v[4:5], v[68:69], 1, v[4:5]
	s_waitcnt lgkmcnt(0)
	global_store_dwordx4 v[4:5], v[6:9], off nt
.LBB0_1018:
	s_or_b64 exec, exec, s[2:3]
	v_add_u32_e32 v3, 40, v2
	v_cmp_gt_i32_e32 vcc, s72, v3
	s_and_saveexec_b64 s[2:3], vcc
	s_cbranch_execz .LBB0_1020
	v_or_b32_e32 v4, 40, v1
	v_lshlrev_b32_e32 v10, 7, v4
	v_lshrrev_b32_e32 v4, 2, v4
	v_xor_b32_e32 v4, v4, v194
	v_lshlrev_b32_e32 v4, 4, v4
	v_and_b32_e32 v4, 0x70, v4
	v_ashrrev_i32_e32 v8, 8, v3
	v_add3_u32 v4, 0, v10, v4
	v_ashrrev_i32_e32 v9, 31, v8
	ds_read_b128 v[4:7], v4
	v_lshlrev_b64 v[8:9], 20, v[8:9]
	s_lshl_b64 s[10:11], s[8:9], 15
	v_lshl_add_u64 v[8:9], s[6:7], 0, v[8:9]
	v_lshl_add_u64 v[8:9], v[8:9], 0, s[10:11]
	v_and_b32_e32 v10, 0x7780, v10
	v_mov_b32_e32 v11, v0
	v_lshl_add_u64 v[8:9], v[8:9], 0, v[10:11]
	v_lshl_add_u64 v[8:9], v[68:69], 1, v[8:9]
	s_waitcnt lgkmcnt(0)
	global_store_dwordx4 v[8:9], v[4:7], off nt
.LBB0_1020:
	s_or_b64 exec, exec, s[2:3]
	v_add_u32_e32 v3, 48, v2
	v_cmp_gt_i32_e32 vcc, s72, v3
	s_and_saveexec_b64 s[2:3], vcc
	s_cbranch_execz .LBB0_1022
	v_or_b32_e32 v4, 48, v1
	v_lshlrev_b32_e32 v10, 7, v4
	v_lshrrev_b32_e32 v4, 2, v4
	v_xor_b32_e32 v4, v4, v194
	v_lshlrev_b32_e32 v4, 4, v4
	v_and_b32_e32 v4, 0x70, v4
	v_ashrrev_i32_e32 v8, 8, v3
	v_add3_u32 v4, 0, v10, v4
	v_ashrrev_i32_e32 v9, 31, v8
	ds_read_b128 v[4:7], v4
	v_lshlrev_b64 v[8:9], 20, v[8:9]
	s_lshl_b64 s[10:11], s[8:9], 15
	v_lshl_add_u64 v[8:9], s[6:7], 0, v[8:9]
	v_lshl_add_u64 v[8:9], v[8:9], 0, s[10:11]
	v_and_b32_e32 v10, 0x7b80, v10
	v_mov_b32_e32 v11, v0
	v_lshl_add_u64 v[8:9], v[8:9], 0, v[10:11]
	v_lshl_add_u64 v[8:9], v[68:69], 1, v[8:9]
	s_waitcnt lgkmcnt(0)
	global_store_dwordx4 v[8:9], v[4:7], off nt
.LBB0_1022:
	s_or_b64 exec, exec, s[2:3]
	v_add_u32_e32 v2, 56, v2
	v_cmp_gt_i32_e32 vcc, s72, v2
	s_and_saveexec_b64 s[2:3], vcc
	s_cbranch_execz .LBB0_975
	v_or_b32_e32 v1, 56, v1
	v_lshlrev_b32_e32 v8, 7, v1
	v_lshrrev_b32_e32 v1, 2, v1
	v_xor_b32_e32 v1, v1, v194
	v_lshlrev_b32_e32 v1, 4, v1
	v_and_b32_e32 v1, 0x70, v1
	v_ashrrev_i32_e32 v2, 8, v2
	v_add3_u32 v1, 0, v8, v1
	v_ashrrev_i32_e32 v3, 31, v2
	ds_read_b128 v[4:7], v1
	v_lshlrev_b64 v[2:3], 20, v[2:3]
	s_lshl_b64 s[8:9], s[8:9], 15
	v_lshl_add_u64 v[2:3], s[6:7], 0, v[2:3]
	v_lshl_add_u64 v[2:3], v[2:3], 0, s[8:9]
	v_and_b32_e32 v8, 0x7f80, v8
	v_mov_b32_e32 v9, v0
	v_lshl_add_u64 v[2:3], v[2:3], 0, v[8:9]
	v_lshl_add_u64 v[2:3], v[68:69], 1, v[2:3]
	s_waitcnt lgkmcnt(0)
	global_store_dwordx4 v[2:3], v[4:7], off nt
	s_branch .LBB0_975

; __device__ __forceinline__ unsigned cvt_pk_bf16(float lo, float hi) { f32x2 v = {lo, hi}; bf16x2_t b = __builtin_convertvector(v, bf16x2_t); return __builtin_bit_cast(unsigned, b); }
; __device__ __forceinline__ void cvt_straight(const float* W, bf16_t* O, long n, int tid, int b0, const float* gvec) {
;     const long stride = (long)((int)gridDim.x - b0) * 512 * 8;
;     for (long i = ((long)((int)blockIdx.x - b0) * 512 + tid) * 8; i < n; i += stride) { const float gk = gvec[i >> 11]; const f32x4 a = *(const f32x4*)(W + i) * gk, b = *(const f32x4*)(W + i + 4) * gk;
;         u32x4 w; w.x = cvt_pk_bf16(a[0], a[1]); w.y = cvt_pk_bf16(a[2], a[3]); w.z = cvt_pk_bf16(b[0], b[1]); w.w = cvt_pk_bf16(b[2], b[3]); *(u32x4*)(O + i) = w; }
; }
.LBB0_1028:
	v_ashrrev_i64 v[8:9], 11, v[6:7]
	v_lshl_add_u64 v[8:9], v[8:9], 2, s[42:43]
	global_load_dword v16, v[8:9], off
	s_nop 0
	global_load_dwordx4 v[8:11], v[2:3], off nt
	global_load_dwordx4 v[12:15], v[2:3], off offset:-16 nt
	v_lshl_add_u64 v[6:7], v[6:7], 0, s[66:67]
	s_mov_b64 s[46:47], 0x3fffff
	v_cmp_lt_i64_e32 vcc, s[46:47], v[6:7]
	v_lshl_add_u64 v[2:3], v[2:3], 0, s[88:89]
	s_or_b64 s[44:45], vcc, s[44:45]
	s_waitcnt vmcnt(0)
	v_pk_mul_f32 v[18:19], v[10:11], v[16:17] op_sel_hi:[1,0]
	v_pk_mul_f32 v[14:15], v[14:15], v[16:17] op_sel_hi:[1,0]
	v_pk_mul_f32 v[12:13], v[12:13], v[16:17] op_sel_hi:[1,0]
	v_pk_mul_f32 v[10:11], v[8:9], v[16:17] op_sel_hi:[1,0]
	v_cvt_pk_bf16_f32 v8, v12, v13
	v_cvt_pk_bf16_f32 v9, v14, v15
	v_cvt_pk_bf16_f32 v10, v10, v11
	v_cvt_pk_bf16_f32 v11, v18, v19
	global_store_dwordx4 v[4:5], v[8:11], off nt
	v_lshl_add_u64 v[4:5], v[4:5], 0, s[96:97]
	s_andn2_b64 exec, exec, s[44:45]
	s_cbranch_execnz .LBB0_1028

; #define LAS __attribute__((address_space(3)))
; __device__ __forceinline__ unsigned cvt_pk_bf16(float lo, float hi) { f32x2 v = {lo, hi}; bf16x2_t b = __builtin_convertvector(v, bf16x2_t); return __builtin_bit_cast(unsigned, b); }
; __device__ __forceinline__ void cvt_tile(const float* W, int ldw, int nvalid, int k0, int n0, bf16_t* WT, int K, int map, int rows_cap, LAS unsigned char* T, int tid, const float* gvec) {
;     ...
;     const int phys = w ^ (lane & 7);
; #pragma unroll
;     for (int hh = 0; hh < 2; ++hh)
; #pragma unroll
;         for (int r = 0; r < 4; ++r)
; #pragma unroll
;             for (int jn = 0; jn < 4; ++jn) *(LAS unsigned*)(T + (256 * hh + 4 * lane + jn) * 128 + phys * 16 + r * 4) = cvt_pk_bf16(v[hh][2 * r][jn], v[hh][2 * r + 1][jn]);
;     __syncthreads();
;     const int kt = k0 >> 6, nkt = K >> 6;
; #pragma unroll
;     for (int it = 0; it < 8; ++it) { const int n = 64 * w + 8 * it + (lane >> 3), c = lane & 7;
;         const u32x4 o = *(const LAS u32x4*)(T + n * 128 + ((c ^ ((n >> 2) & 7)) << 4));
;         const int ng = n0 + n; const int d = map == 0 ? ng : (ng / 128) * 256 + (ng % 128) + (map == 2 ? 128 : 0);
;         if (d < rows_cap) *(u32x4*)(WT + ((size_t)(d >> 8) * nkt + kt) * 16384 + (d & 255) * 64 + 8 * c) = o; }
;     __syncthreads();
.LBB0_1064:
	s_or_b64 exec, exec, s[2:3]
	v_xor_b32_e32 v1, s52, v79
	s_waitcnt vmcnt(0)
	v_cvt_pk_bf16_f32 v2, v2, v6
	v_lshl_add_u32 v1, v1, 4, v82
	v_cvt_pk_bf16_f32 v6, v3, v7
	v_cvt_pk_bf16_f32 v84, v4, v8
	v_cvt_pk_bf16_f32 v88, v5, v9
	v_cvt_pk_bf16_f32 v3, v14, v10
	v_cvt_pk_bf16_f32 v7, v15, v11
	v_cvt_pk_bf16_f32 v4, v22, v18
	v_cvt_pk_bf16_f32 v8, v23, v19
	v_cvt_pk_bf16_f32 v5, v30, v26
	v_cvt_pk_bf16_f32 v9, v31, v27
	v_cvt_pk_bf16_f32 v85, v16, v12
	v_cvt_pk_bf16_f32 v89, v17, v13
	v_cvt_pk_bf16_f32 v86, v24, v20
	v_cvt_pk_bf16_f32 v90, v25, v21
	ds_write_b128 v1, v[2:5]
	ds_write_b128 v1, v[6:9] offset:128
	v_cvt_pk_bf16_f32 v87, v32, v28
	v_cvt_pk_bf16_f32 v91, v33, v29
	v_cvt_pk_bf16_f32 v2, v34, v38
	v_cvt_pk_bf16_f32 v6, v35, v39
	v_cvt_pk_bf16_f32 v10, v36, v40
	v_cvt_pk_bf16_f32 v14, v37, v41
	v_cvt_pk_bf16_f32 v3, v46, v42
	v_cvt_pk_bf16_f32 v7, v47, v43
	v_cvt_pk_bf16_f32 v11, v48, v44
	v_cvt_pk_bf16_f32 v15, v49, v45
	v_cvt_pk_bf16_f32 v4, v54, v50
	v_cvt_pk_bf16_f32 v8, v55, v51
	v_cvt_pk_bf16_f32 v12, v56, v52
	v_cvt_pk_bf16_f32 v16, v57, v53
	v_cvt_pk_bf16_f32 v5, v62, v58
	v_cvt_pk_bf16_f32 v9, v63, v59
	v_cvt_pk_bf16_f32 v13, v64, v60
	v_cvt_pk_bf16_f32 v17, v65, v61
	s_and_b32 s2, s45, 0xffffffc0
	ds_write_b128 v1, v[84:87] offset:256
	ds_write_b128 v1, v[88:91] offset:384
	ds_write_b128 v1, v[2:5] offset:32768
	ds_write_b128 v1, v[6:9] offset:32896
	ds_write_b128 v1, v[10:13] offset:33024
	ds_write_b128 v1, v[14:17] offset:33152
	v_or_b32_e32 v1, s2, v80
	s_sub_i32 s2, s2, s51
	s_add_i32 s2, s2, s49
	v_add_u32_e32 v2, s2, v80
	s_ashr_i32 s45, s44, 31
	v_cmp_gt_i32_e32 vcc, s40, v2
	v_lshlrev_b32_e32 v3, 7, v1
	s_waitcnt lgkmcnt(0)
	s_barrier
	s_and_saveexec_b64 s[2:3], vcc
	s_cbranch_execz .LBB0_1066
	v_ashrrev_i32_e32 v8, 8, v2
	v_add_u32_e32 v4, v81, v3
	v_ashrrev_i32_e32 v9, 31, v8
	ds_read_b128 v[4:7], v4
	v_lshlrev_b64 v[8:9], 20, v[8:9]
	s_lshl_b64 s[46:47], s[44:45], 15
	v_lshl_add_u64 v[8:9], s[42:43], 0, v[8:9]
	v_lshl_add_u64 v[8:9], v[8:9], 0, s[46:47]
	v_and_b32_e32 v10, 0x6380, v3
	v_mov_b32_e32 v11, v0
	v_lshl_add_u64 v[8:9], v[8:9], 0, v[10:11]
	v_lshl_add_u64 v[8:9], v[68:69], 1, v[8:9]
	s_waitcnt lgkmcnt(0)
	global_store_dwordx4 v[8:9], v[4:7], off nt
.LBB0_1066:
	s_or_b64 exec, exec, s[2:3]
	s_nop 0
	v_add_u32_e32 v4, 8, v2
	v_cmp_gt_i32_e32 vcc, s40, v4
	s_and_saveexec_b64 s[2:3], vcc
	s_cbranch_execz .LBB0_1068
	v_or_b32_e32 v5, 8, v1
	v_lshlrev_b32_e32 v10, 7, v5
	v_lshrrev_b32_e32 v5, 2, v5
	v_xor_b32_e32 v5, v5, v194
	v_lshlrev_b32_e32 v5, 4, v5
	v_and_b32_e32 v5, 0x70, v5
	v_add3_u32 v5, 0, v10, v5
	v_ashrrev_i32_e32 v4, 8, v4
	ds_read_b128 v[6:9], v5
	v_ashrrev_i32_e32 v5, 31, v4
	v_lshlrev_b64 v[4:5], 20, v[4:5]
	s_lshl_b64 s[46:47], s[44:45], 15
	v_lshl_add_u64 v[4:5], s[42:43], 0, v[4:5]
	v_lshl_add_u64 v[4:5], v[4:5], 0, s[46:47]
	v_and_b32_e32 v10, 0x6780, v10
	v_mov_b32_e32 v11, v0
	v_lshl_add_u64 v[4:5], v[4:5], 0, v[10:11]
	v_lshl_add_u64 v[4:5], v[68:69], 1, v[4:5]
	s_waitcnt lgkmcnt(0)
	global_store_dwordx4 v[4:5], v[6:9], off nt
.LBB0_1068:
	s_or_b64 exec, exec, s[2:3]
	v_add_u32_e32 v4, 16, v2
	v_cmp_gt_i32_e32 vcc, s40, v4
	s_and_saveexec_b64 s[2:3], vcc
	s_cbranch_execz .LBB0_1070
	v_or_b32_e32 v5, 16, v1
	v_lshlrev_b32_e32 v10, 7, v5
	v_lshrrev_b32_e32 v5, 2, v5
	v_xor_b32_e32 v5, v5, v194
	v_lshlrev_b32_e32 v5, 4, v5
	v_and_b32_e32 v5, 0x70, v5
	v_add3_u32 v5, 0, v10, v5
	v_ashrrev_i32_e32 v4, 8, v4
	ds_read_b128 v[6:9], v5
	v_ashrrev_i32_e32 v5, 31, v4
	v_lshlrev_b64 v[4:5], 20, v[4:5]
	s_lshl_b64 s[46:47], s[44:45], 15
	v_lshl_add_u64 v[4:5], s[42:43], 0, v[4:5]
	v_lshl_add_u64 v[4:5], v[4:5], 0, s[46:47]
	v_and_b32_e32 v10, 0x6b80, v10
	v_mov_b32_e32 v11, v0
	v_lshl_add_u64 v[4:5], v[4:5], 0, v[10:11]
	v_lshl_add_u64 v[4:5], v[68:69], 1, v[4:5]
	s_waitcnt lgkmcnt(0)
	global_store_dwordx4 v[4:5], v[6:9], off nt
; #define LAS __attribute__((address_space(3)))
; __device__ __forceinline__ void cvt_tile(const float* W, int ldw, int nvalid, int k0, int n0, bf16_t* WT, int K, int map, int rows_cap, LAS unsigned char* T, int tid, const float* gvec) {
;     ...
;     for (int it = 0; it < 8; ++it) { const int n = 64 * w + 8 * it + (lane >> 3), c = lane & 7;
;         const u32x4 o = *(const LAS u32x4*)(T + n * 128 + ((c ^ ((n >> 2) & 7)) << 4));
;         const int ng = n0 + n; const int d = map == 0 ? ng : (ng / 128) * 256 + (ng % 128) + (map == 2 ? 128 : 0);
;         if (d < rows_cap) *(u32x4*)(WT + ((size_t)(d >> 8) * nkt + kt) * 16384 + (d & 255) * 64 + 8 * c) = o; }
;     __syncthreads();
.LBB0_1070:
	s_or_b64 exec, exec, s[2:3]
	v_add_u32_e32 v4, 24, v2
	v_cmp_gt_i32_e32 vcc, s40, v4
	s_and_saveexec_b64 s[2:3], vcc
	s_cbranch_execz .LBB0_1072
	v_or_b32_e32 v5, 24, v1
	v_lshlrev_b32_e32 v10, 7, v5
	v_lshrrev_b32_e32 v5, 2, v5
	v_xor_b32_e32 v5, v5, v194
	v_lshlrev_b32_e32 v5, 4, v5
	v_and_b32_e32 v5, 0x70, v5
	v_add3_u32 v5, 0, v10, v5
	v_ashrrev_i32_e32 v4, 8, v4
	ds_read_b128 v[6:9], v5
	v_ashrrev_i32_e32 v5, 31, v4
	v_lshlrev_b64 v[4:5], 20, v[4:5]
	s_lshl_b64 s[46:47], s[44:45], 15
	v_lshl_add_u64 v[4:5], s[42:43], 0, v[4:5]
	v_lshl_add_u64 v[4:5], v[4:5], 0, s[46:47]
	v_and_b32_e32 v10, 0x6f80, v10
	v_mov_b32_e32 v11, v0
	v_lshl_add_u64 v[4:5], v[4:5], 0, v[10:11]
	v_lshl_add_u64 v[4:5], v[68:69], 1, v[4:5]
	s_waitcnt lgkmcnt(0)
	global_store_dwordx4 v[4:5], v[6:9], off nt
.LBB0_1072:
	s_or_b64 exec, exec, s[2:3]
	v_add_u32_e32 v4, 32, v2
	v_cmp_gt_i32_e32 vcc, s40, v4
	s_and_saveexec_b64 s[2:3], vcc
	s_cbranch_execz .LBB0_1074
	v_or_b32_e32 v5, 0x1000, v3
	v_add_u32_e32 v5, v81, v5
	v_ashrrev_i32_e32 v4, 8, v4
	ds_read_b128 v[6:9], v5
	v_ashrrev_i32_e32 v5, 31, v4
	v_lshlrev_b64 v[4:5], 20, v[4:5]
	s_lshl_b64 s[46:47], s[44:45], 15
	v_lshl_add_u64 v[4:5], s[42:43], 0, v[4:5]
	v_lshl_add_u64 v[4:5], v[4:5], 0, s[46:47]
	v_bitop3_b32 v10, v3, s74, v216 bitop3:0xc8
	v_mov_b32_e32 v11, v0
	v_lshl_add_u64 v[4:5], v[4:5], 0, v[10:11]
	v_lshl_add_u64 v[4:5], v[68:69], 1, v[4:5]
	s_waitcnt lgkmcnt(0)
	global_store_dwordx4 v[4:5], v[6:9], off nt
.LBB0_1074:
	s_or_b64 exec, exec, s[2:3]
	v_add_u32_e32 v3, 40, v2
	v_cmp_gt_i32_e32 vcc, s40, v3
	s_and_saveexec_b64 s[2:3], vcc
	s_cbranch_execz .LBB0_1076
	v_or_b32_e32 v4, 40, v1
	v_lshlrev_b32_e32 v10, 7, v4
	v_lshrrev_b32_e32 v4, 2, v4
	v_xor_b32_e32 v4, v4, v194
	v_lshlrev_b32_e32 v4, 4, v4
	v_and_b32_e32 v4, 0x70, v4
	v_ashrrev_i32_e32 v8, 8, v3
	v_add3_u32 v4, 0, v10, v4
	v_ashrrev_i32_e32 v9, 31, v8
	ds_read_b128 v[4:7], v4
	v_lshlrev_b64 v[8:9], 20, v[8:9]
	s_lshl_b64 s[46:47], s[44:45], 15
	v_lshl_add_u64 v[8:9], s[42:43], 0, v[8:9]
	v_lshl_add_u64 v[8:9], v[8:9], 0, s[46:47]
	v_and_b32_e32 v10, 0x7780, v10
	v_mov_b32_e32 v11, v0
	v_lshl_add_u64 v[8:9], v[8:9], 0, v[10:11]
	v_lshl_add_u64 v[8:9], v[68:69], 1, v[8:9]
	s_waitcnt lgkmcnt(0)
	global_store_dwordx4 v[8:9], v[4:7], off nt
.LBB0_1076:
	s_or_b64 exec, exec, s[2:3]
	v_add_u32_e32 v3, 48, v2
	v_cmp_gt_i32_e32 vcc, s40, v3
	s_and_saveexec_b64 s[2:3], vcc
	s_cbranch_execz .LBB0_1078
	v_or_b32_e32 v4, 48, v1
	v_lshlrev_b32_e32 v10, 7, v4
	v_lshrrev_b32_e32 v4, 2, v4
	v_xor_b32_e32 v4, v4, v194
	v_lshlrev_b32_e32 v4, 4, v4
	v_and_b32_e32 v4, 0x70, v4
	v_ashrrev_i32_e32 v8, 8, v3
	v_add3_u32 v4, 0, v10, v4
	v_ashrrev_i32_e32 v9, 31, v8
	ds_read_b128 v[4:7], v4
	v_lshlrev_b64 v[8:9], 20, v[8:9]
	s_lshl_b64 s[46:47], s[44:45], 15
	v_lshl_add_u64 v[8:9], s[42:43], 0, v[8:9]
	v_lshl_add_u64 v[8:9], v[8:9], 0, s[46:47]
	v_and_b32_e32 v10, 0x7b80, v10
	v_mov_b32_e32 v11, v0
	v_lshl_add_u64 v[8:9], v[8:9], 0, v[10:11]
	v_lshl_add_u64 v[8:9], v[68:69], 1, v[8:9]
	s_waitcnt lgkmcnt(0)
	global_store_dwordx4 v[8:9], v[4:7], off nt
.LBB0_1078:
	s_or_b64 exec, exec, s[2:3]
	v_add_u32_e32 v2, 56, v2
	v_cmp_gt_i32_e32 vcc, s40, v2
	s_and_saveexec_b64 s[2:3], vcc
	s_cbranch_execz .LBB0_1031
	v_or_b32_e32 v1, 56, v1
	v_lshlrev_b32_e32 v8, 7, v1
	v_lshrrev_b32_e32 v1, 2, v1
	v_xor_b32_e32 v1, v1, v194
	v_lshlrev_b32_e32 v1, 4, v1
	v_and_b32_e32 v1, 0x70, v1
	v_ashrrev_i32_e32 v2, 8, v2
	v_add3_u32 v1, 0, v8, v1
	v_ashrrev_i32_e32 v3, 31, v2
	ds_read_b128 v[4:7], v1
	v_lshlrev_b64 v[2:3], 20, v[2:3]
	s_lshl_b64 s[44:45], s[44:45], 15
	v_lshl_add_u64 v[2:3], s[42:43], 0, v[2:3]
	v_lshl_add_u64 v[2:3], v[2:3], 0, s[44:45]
	v_and_b32_e32 v8, 0x7f80, v8
	v_mov_b32_e32 v9, v0
	v_lshl_add_u64 v[2:3], v[2:3], 0, v[8:9]
	v_lshl_add_u64 v[2:3], v[68:69], 1, v[2:3]
	s_waitcnt lgkmcnt(0)
	global_store_dwordx4 v[2:3], v[4:7], off nt
	s_branch .LBB0_1031

; #define LAS __attribute__((address_space(3)))
; __device__ __forceinline__ unsigned cvt_pk_bf16(float lo, float hi) { f32x2 v = {lo, hi}; bf16x2_t b = __builtin_convertvector(v, bf16x2_t); return __builtin_bit_cast(unsigned, b); }
; __device__ __forceinline__ void cvt_tile(const float* W, int ldw, int nvalid, int k0, int n0, bf16_t* WT, int K, int map, int rows_cap, LAS unsigned char* T, int tid, const float* gvec) {
;     ...
;     const int phys = w ^ (lane & 7);
; #pragma unroll
;     for (int hh = 0; hh < 2; ++hh)
; #pragma unroll
;         for (int r = 0; r < 4; ++r)
; #pragma unroll
;             for (int jn = 0; jn < 4; ++jn) *(LAS unsigned*)(T + (256 * hh + 4 * lane + jn) * 128 + phys * 16 + r * 4) = cvt_pk_bf16(v[hh][2 * r][jn], v[hh][2 * r + 1][jn]);
;     __syncthreads();
;     const int kt = k0 >> 6, nkt = K >> 6;
; #pragma unroll
;     for (int it = 0; it < 8; ++it) { const int n = 64 * w + 8 * it + (lane >> 3), c = lane & 7;
;         const u32x4 o = *(const LAS u32x4*)(T + n * 128 + ((c ^ ((n >> 2) & 7)) << 4));
;         const int ng = n0 + n; const int d = map == 0 ? ng : (ng / 128) * 256 + (ng % 128) + (map == 2 ? 128 : 0);
;         if (d < rows_cap) *(u32x4*)(WT + ((size_t)(d >> 8) * nkt + kt) * 16384 + (d & 255) * 64 + 8 * c) = o; }
;     __syncthreads();
.LBB0_1115:
	s_or_b64 exec, exec, s[2:3]
	v_xor_b32_e32 v1, s52, v79
	s_waitcnt vmcnt(0)
	v_cvt_pk_bf16_f32 v2, v2, v6
	v_lshl_add_u32 v1, v1, 4, v82
	v_cvt_pk_bf16_f32 v6, v3, v7
	v_cvt_pk_bf16_f32 v84, v4, v8
	v_cvt_pk_bf16_f32 v88, v5, v9
	v_cvt_pk_bf16_f32 v3, v14, v10
	v_cvt_pk_bf16_f32 v7, v15, v11
	v_cvt_pk_bf16_f32 v4, v22, v18
	v_cvt_pk_bf16_f32 v8, v23, v19
	v_cvt_pk_bf16_f32 v5, v30, v26
	v_cvt_pk_bf16_f32 v9, v31, v27
	v_cvt_pk_bf16_f32 v85, v16, v12
	v_cvt_pk_bf16_f32 v89, v17, v13
	v_cvt_pk_bf16_f32 v86, v24, v20
	v_cvt_pk_bf16_f32 v90, v25, v21
	ds_write_b128 v1, v[2:5]
	ds_write_b128 v1, v[6:9] offset:128
	v_cvt_pk_bf16_f32 v87, v32, v28
	v_cvt_pk_bf16_f32 v91, v33, v29
	v_cvt_pk_bf16_f32 v2, v34, v38
	v_cvt_pk_bf16_f32 v6, v35, v39
	v_cvt_pk_bf16_f32 v10, v36, v40
	v_cvt_pk_bf16_f32 v14, v37, v41
	v_cvt_pk_bf16_f32 v3, v46, v42
	v_cvt_pk_bf16_f32 v7, v47, v43
	v_cvt_pk_bf16_f32 v11, v48, v44
	v_cvt_pk_bf16_f32 v15, v49, v45
	v_cvt_pk_bf16_f32 v4, v54, v50
	v_cvt_pk_bf16_f32 v8, v55, v51
	v_cvt_pk_bf16_f32 v12, v56, v52
	v_cvt_pk_bf16_f32 v16, v57, v53
	v_cvt_pk_bf16_f32 v5, v62, v58
	v_cvt_pk_bf16_f32 v9, v63, v59
	v_cvt_pk_bf16_f32 v13, v64, v60
	v_cvt_pk_bf16_f32 v17, v65, v61
	s_and_b32 s2, s45, 0xffffffc0
	ds_write_b128 v1, v[84:87] offset:256
	ds_write_b128 v1, v[88:91] offset:384
	ds_write_b128 v1, v[2:5] offset:32768
	ds_write_b128 v1, v[6:9] offset:32896
	ds_write_b128 v1, v[10:13] offset:33024
	ds_write_b128 v1, v[14:17] offset:33152
	v_or_b32_e32 v1, s2, v80
	s_sub_i32 s2, s2, s51
	s_add_i32 s2, s2, s49
	v_add_u32_e32 v2, s2, v80
	s_ashr_i32 s45, s44, 31
	v_cmp_gt_i32_e32 vcc, s72, v2
	v_lshlrev_b32_e32 v3, 7, v1
	s_waitcnt lgkmcnt(0)
	s_barrier
	s_and_saveexec_b64 s[2:3], vcc
	s_cbranch_execz .LBB0_1117
	v_ashrrev_i32_e32 v8, 8, v2
	v_add_u32_e32 v4, v81, v3
	v_ashrrev_i32_e32 v9, 31, v8
	ds_read_b128 v[4:7], v4
	v_lshlrev_b64 v[8:9], 20, v[8:9]
	s_lshl_b64 s[46:47], s[44:45], 15
	v_lshl_add_u64 v[8:9], s[42:43], 0, v[8:9]
	v_lshl_add_u64 v[8:9], v[8:9], 0, s[46:47]
	v_and_b32_e32 v10, 0x6380, v3
	v_mov_b32_e32 v11, v0
	v_lshl_add_u64 v[8:9], v[8:9], 0, v[10:11]
	v_lshl_add_u64 v[8:9], v[68:69], 1, v[8:9]
	s_waitcnt lgkmcnt(0)
	global_store_dwordx4 v[8:9], v[4:7], off nt
.LBB0_1117:
	s_or_b64 exec, exec, s[2:3]
	s_nop 0
	v_add_u32_e32 v4, 8, v2
	v_cmp_gt_i32_e32 vcc, s72, v4
	s_and_saveexec_b64 s[2:3], vcc
	s_cbranch_execz .LBB0_1119
	v_or_b32_e32 v5, 8, v1
	v_lshlrev_b32_e32 v10, 7, v5
	v_lshrrev_b32_e32 v5, 2, v5
	v_xor_b32_e32 v5, v5, v194
	v_lshlrev_b32_e32 v5, 4, v5
	v_and_b32_e32 v5, 0x70, v5
	v_add3_u32 v5, 0, v10, v5
	v_ashrrev_i32_e32 v4, 8, v4
	ds_read_b128 v[6:9], v5
	v_ashrrev_i32_e32 v5, 31, v4
	v_lshlrev_b64 v[4:5], 20, v[4:5]
	s_lshl_b64 s[46:47], s[44:45], 15
	v_lshl_add_u64 v[4:5], s[42:43], 0, v[4:5]
	v_lshl_add_u64 v[4:5], v[4:5], 0, s[46:47]
	v_and_b32_e32 v10, 0x6780, v10
	v_mov_b32_e32 v11, v0
	v_lshl_add_u64 v[4:5], v[4:5], 0, v[10:11]
	v_lshl_add_u64 v[4:5], v[68:69], 1, v[4:5]
	s_waitcnt lgkmcnt(0)
	global_store_dwordx4 v[4:5], v[6:9], off nt
.LBB0_1119:
	s_or_b64 exec, exec, s[2:3]
	v_add_u32_e32 v4, 16, v2
	v_cmp_gt_i32_e32 vcc, s72, v4
	s_and_saveexec_b64 s[2:3], vcc
	s_cbranch_execz .LBB0_1121
	v_or_b32_e32 v5, 16, v1
	v_lshlrev_b32_e32 v10, 7, v5
	v_lshrrev_b32_e32 v5, 2, v5
	v_xor_b32_e32 v5, v5, v194
	v_lshlrev_b32_e32 v5, 4, v5
	v_and_b32_e32 v5, 0x70, v5
	v_add3_u32 v5, 0, v10, v5
	v_ashrrev_i32_e32 v4, 8, v4
	ds_read_b128 v[6:9], v5
	v_ashrrev_i32_e32 v5, 31, v4
	v_lshlrev_b64 v[4:5], 20, v[4:5]
	s_lshl_b64 s[46:47], s[44:45], 15
	v_lshl_add_u64 v[4:5], s[42:43], 0, v[4:5]
	v_lshl_add_u64 v[4:5], v[4:5], 0, s[46:47]
	v_and_b32_e32 v10, 0x6b80, v10
	v_mov_b32_e32 v11, v0
	v_lshl_add_u64 v[4:5], v[4:5], 0, v[10:11]
	v_lshl_add_u64 v[4:5], v[68:69], 1, v[4:5]
	s_waitcnt lgkmcnt(0)
	global_store_dwordx4 v[4:5], v[6:9], off nt
; #define LAS __attribute__((address_space(3)))
; __device__ __forceinline__ void cvt_tile(const float* W, int ldw, int nvalid, int k0, int n0, bf16_t* WT, int K, int map, int rows_cap, LAS unsigned char* T, int tid, const float* gvec) {
;     ...
;     for (int it = 0; it < 8; ++it) { const int n = 64 * w + 8 * it + (lane >> 3), c = lane & 7;
;         const u32x4 o = *(const LAS u32x4*)(T + n * 128 + ((c ^ ((n >> 2) & 7)) << 4));
;         const int ng = n0 + n; const int d = map == 0 ? ng : (ng / 128) * 256 + (ng % 128) + (map == 2 ? 128 : 0);
;         if (d < rows_cap) *(u32x4*)(WT + ((size_t)(d >> 8) * nkt + kt) * 16384 + (d & 255) * 64 + 8 * c) = o; }
;     __syncthreads();
.LBB0_1121:
	s_or_b64 exec, exec, s[2:3]
	v_add_u32_e32 v4, 24, v2
	v_cmp_gt_i32_e32 vcc, s72, v4
	s_and_saveexec_b64 s[2:3], vcc
	s_cbranch_execz .LBB0_1123
	v_or_b32_e32 v5, 24, v1
	v_lshlrev_b32_e32 v10, 7, v5
	v_lshrrev_b32_e32 v5, 2, v5
	v_xor_b32_e32 v5, v5, v194
	v_lshlrev_b32_e32 v5, 4, v5
	v_and_b32_e32 v5, 0x70, v5
	v_add3_u32 v5, 0, v10, v5
	v_ashrrev_i32_e32 v4, 8, v4
	ds_read_b128 v[6:9], v5
	v_ashrrev_i32_e32 v5, 31, v4
	v_lshlrev_b64 v[4:5], 20, v[4:5]
	s_lshl_b64 s[46:47], s[44:45], 15
	v_lshl_add_u64 v[4:5], s[42:43], 0, v[4:5]
	v_lshl_add_u64 v[4:5], v[4:5], 0, s[46:47]
	v_and_b32_e32 v10, 0x6f80, v10
	v_mov_b32_e32 v11, v0
	v_lshl_add_u64 v[4:5], v[4:5], 0, v[10:11]
	v_lshl_add_u64 v[4:5], v[68:69], 1, v[4:5]
	s_waitcnt lgkmcnt(0)
	global_store_dwordx4 v[4:5], v[6:9], off nt
.LBB0_1123:
	s_or_b64 exec, exec, s[2:3]
	v_add_u32_e32 v4, 32, v2
	v_cmp_gt_i32_e32 vcc, s72, v4
	s_and_saveexec_b64 s[2:3], vcc
	s_cbranch_execz .LBB0_1125
	v_or_b32_e32 v5, 0x1000, v3
	v_add_u32_e32 v5, v81, v5
	v_ashrrev_i32_e32 v4, 8, v4
	ds_read_b128 v[6:9], v5
	v_ashrrev_i32_e32 v5, 31, v4
	v_lshlrev_b64 v[4:5], 20, v[4:5]
	s_lshl_b64 s[46:47], s[44:45], 15
	v_lshl_add_u64 v[4:5], s[42:43], 0, v[4:5]
	v_lshl_add_u64 v[4:5], v[4:5], 0, s[46:47]
	v_bitop3_b32 v10, v3, s74, v216 bitop3:0xc8
	v_mov_b32_e32 v11, v0
	v_lshl_add_u64 v[4:5], v[4:5], 0, v[10:11]
	v_lshl_add_u64 v[4:5], v[68:69], 1, v[4:5]
	s_waitcnt lgkmcnt(0)
	global_store_dwordx4 v[4:5], v[6:9], off nt
.LBB0_1125:
	s_or_b64 exec, exec, s[2:3]
	v_add_u32_e32 v3, 40, v2
	v_cmp_gt_i32_e32 vcc, s72, v3
	s_and_saveexec_b64 s[2:3], vcc
	s_cbranch_execz .LBB0_1127
	v_or_b32_e32 v4, 40, v1
	v_lshlrev_b32_e32 v10, 7, v4
	v_lshrrev_b32_e32 v4, 2, v4
	v_xor_b32_e32 v4, v4, v194
	v_lshlrev_b32_e32 v4, 4, v4
	v_and_b32_e32 v4, 0x70, v4
	v_ashrrev_i32_e32 v8, 8, v3
	v_add3_u32 v4, 0, v10, v4
	v_ashrrev_i32_e32 v9, 31, v8
	ds_read_b128 v[4:7], v4
	v_lshlrev_b64 v[8:9], 20, v[8:9]
	s_lshl_b64 s[46:47], s[44:45], 15
	v_lshl_add_u64 v[8:9], s[42:43], 0, v[8:9]
	v_lshl_add_u64 v[8:9], v[8:9], 0, s[46:47]
	v_and_b32_e32 v10, 0x7780, v10
	v_mov_b32_e32 v11, v0
	v_lshl_add_u64 v[8:9], v[8:9], 0, v[10:11]
	v_lshl_add_u64 v[8:9], v[68:69], 1, v[8:9]
	s_waitcnt lgkmcnt(0)
	global_store_dwordx4 v[8:9], v[4:7], off nt
.LBB0_1127:
	s_or_b64 exec, exec, s[2:3]
	v_add_u32_e32 v3, 48, v2
	v_cmp_gt_i32_e32 vcc, s72, v3
	s_and_saveexec_b64 s[2:3], vcc
	s_cbranch_execz .LBB0_1129
	v_or_b32_e32 v4, 48, v1
	v_lshlrev_b32_e32 v10, 7, v4
	v_lshrrev_b32_e32 v4, 2, v4
	v_xor_b32_e32 v4, v4, v194
	v_lshlrev_b32_e32 v4, 4, v4
	v_and_b32_e32 v4, 0x70, v4
	v_ashrrev_i32_e32 v8, 8, v3
	v_add3_u32 v4, 0, v10, v4
	v_ashrrev_i32_e32 v9, 31, v8
	ds_read_b128 v[4:7], v4
	v_lshlrev_b64 v[8:9], 20, v[8:9]
	s_lshl_b64 s[46:47], s[44:45], 15
	v_lshl_add_u64 v[8:9], s[42:43], 0, v[8:9]
	v_lshl_add_u64 v[8:9], v[8:9], 0, s[46:47]
	v_and_b32_e32 v10, 0x7b80, v10
	v_mov_b32_e32 v11, v0
	v_lshl_add_u64 v[8:9], v[8:9], 0, v[10:11]
	v_lshl_add_u64 v[8:9], v[68:69], 1, v[8:9]
	s_waitcnt lgkmcnt(0)
	global_store_dwordx4 v[8:9], v[4:7], off nt
.LBB0_1129:
	s_or_b64 exec, exec, s[2:3]
	v_add_u32_e32 v2, 56, v2
	v_cmp_gt_i32_e32 vcc, s72, v2
	s_and_saveexec_b64 s[2:3], vcc
	s_cbranch_execz .LBB0_1082
	v_or_b32_e32 v1, 56, v1
	v_lshlrev_b32_e32 v8, 7, v1
	v_lshrrev_b32_e32 v1, 2, v1
	v_xor_b32_e32 v1, v1, v194
	v_lshlrev_b32_e32 v1, 4, v1
	v_and_b32_e32 v1, 0x70, v1
	v_ashrrev_i32_e32 v2, 8, v2
	v_add3_u32 v1, 0, v8, v1
	v_ashrrev_i32_e32 v3, 31, v2
	ds_read_b128 v[4:7], v1
	v_lshlrev_b64 v[2:3], 20, v[2:3]
	s_lshl_b64 s[44:45], s[44:45], 15
	v_lshl_add_u64 v[2:3], s[42:43], 0, v[2:3]
	v_lshl_add_u64 v[2:3], v[2:3], 0, s[44:45]
	v_and_b32_e32 v8, 0x7f80, v8
	v_mov_b32_e32 v9, v0
	v_lshl_add_u64 v[2:3], v[2:3], 0, v[8:9]
	v_lshl_add_u64 v[2:3], v[68:69], 1, v[2:3]
	s_waitcnt lgkmcnt(0)
	global_store_dwordx4 v[2:3], v[4:7], off nt
	s_branch .LBB0_1082

; #define LAS __attribute__((address_space(3)))
; __device__ __forceinline__ unsigned cvt_pk_bf16(float lo, float hi) { f32x2 v = {lo, hi}; bf16x2_t b = __builtin_convertvector(v, bf16x2_t); return __builtin_bit_cast(unsigned, b); }
; __device__ __forceinline__ void cvt_tile(const float* W, int ldw, int nvalid, int k0, int n0, bf16_t* WT, int K, int map, int rows_cap, LAS unsigned char* T, int tid, const float* gvec) {
;     ...
;     const int phys = w ^ (lane & 7);
; #pragma unroll
;     for (int hh = 0; hh < 2; ++hh)
; #pragma unroll
;         for (int r = 0; r < 4; ++r)
; #pragma unroll
;             for (int jn = 0; jn < 4; ++jn) *(LAS unsigned*)(T + (256 * hh + 4 * lane + jn) * 128 + phys * 16 + r * 4) = cvt_pk_bf16(v[hh][2 * r][jn], v[hh][2 * r + 1][jn]);
;     __syncthreads();
;     const int kt = k0 >> 6, nkt = K >> 6;
; #pragma unroll
;     for (int it = 0; it < 8; ++it) { const int n = 64 * w + 8 * it + (lane >> 3), c = lane & 7;
;         const u32x4 o = *(const LAS u32x4*)(T + n * 128 + ((c ^ ((n >> 2) & 7)) << 4));
;         const int ng = n0 + n; const int d = map == 0 ? ng : (ng / 128) * 256 + (ng % 128) + (map == 2 ? 128 : 0);
;         if (d < rows_cap) *(u32x4*)(WT + ((size_t)(d >> 8) * nkt + kt) * 16384 + (d & 255) * 64 + 8 * c) = o; }
;     __syncthreads();
.LBB0_1168:
	v_xor_b32_e32 v1, s53, v79
	s_waitcnt vmcnt(0)
	v_cvt_pk_bf16_f32 v2, v4, v8
	v_lshl_add_u32 v1, v1, 4, v82
	v_cvt_pk_bf16_f32 v8, v5, v9
	v_cvt_pk_bf16_f32 v84, v6, v10
	v_cvt_pk_bf16_f32 v88, v7, v11
	v_cvt_pk_bf16_f32 v3, v12, v16
	v_cvt_pk_bf16_f32 v9, v13, v17
	v_cvt_pk_bf16_f32 v4, v20, v28
	v_cvt_pk_bf16_f32 v10, v21, v29
	v_cvt_pk_bf16_f32 v5, v24, v32
	v_cvt_pk_bf16_f32 v11, v25, v33
	v_cvt_pk_bf16_f32 v85, v14, v18
	v_cvt_pk_bf16_f32 v89, v15, v19
	v_cvt_pk_bf16_f32 v86, v22, v30
	v_cvt_pk_bf16_f32 v90, v23, v31
	ds_write_b128 v1, v[2:5]
	ds_write_b128 v1, v[8:11] offset:128
	v_cvt_pk_bf16_f32 v87, v26, v34
	v_cvt_pk_bf16_f32 v91, v27, v35
	v_cvt_pk_bf16_f32 v2, v36, v40
	v_cvt_pk_bf16_f32 v6, v37, v41
	v_cvt_pk_bf16_f32 v10, v38, v42
	v_cvt_pk_bf16_f32 v14, v39, v43
	v_cvt_pk_bf16_f32 v3, v44, v48
	v_cvt_pk_bf16_f32 v7, v45, v49
	v_cvt_pk_bf16_f32 v11, v46, v50
	v_cvt_pk_bf16_f32 v15, v47, v51
	v_cvt_pk_bf16_f32 v4, v52, v60
	v_cvt_pk_bf16_f32 v8, v53, v61
	v_cvt_pk_bf16_f32 v12, v54, v62
	v_cvt_pk_bf16_f32 v16, v55, v63
	v_cvt_pk_bf16_f32 v5, v56, v64
	v_cvt_pk_bf16_f32 v9, v57, v65
	v_cvt_pk_bf16_f32 v13, v58, v66
	v_cvt_pk_bf16_f32 v17, v59, v67
	s_and_b32 s2, s45, 0xffffffc0
	s_mul_i32 s3, s44, 0x1600
	ds_write_b128 v1, v[84:87] offset:256
	ds_write_b128 v1, v[88:91] offset:384
	ds_write_b128 v1, v[2:5] offset:32768
	ds_write_b128 v1, v[6:9] offset:32896
	ds_write_b128 v1, v[10:13] offset:33024
	ds_write_b128 v1, v[14:17] offset:33152
	v_or_b32_e32 v1, s2, v80
	s_sub_i32 s2, s2, s3
	s_add_i32 s2, s2, s51
	v_add_u32_e32 v2, s2, v80
	v_ashrrev_i32_e32 v3, 31, v2
	v_lshrrev_b32_e32 v3, 25, v3
	v_add_u32_e32 v3, v2, v3
	v_lshlrev_b32_e32 v4, 1, v3
	v_and_b32_e32 v3, 0xffffff80, v3
	v_and_b32_e32 v5, 0xffffff00, v4
	v_sub_u32_e32 v4, v2, v3
	v_add_u32_e32 v5, v5, v4
	s_ashr_i32 s45, s44, 31
	v_cmp_gt_i32_e32 vcc, s84, v5
	v_lshl_add_u32 v3, v1, 7, v81
	s_waitcnt lgkmcnt(0)
	s_barrier
	s_and_saveexec_b64 s[2:3], vcc
	s_cbranch_execz .LBB0_1170
	v_ashrrev_i32_e32 v10, 8, v5
	v_ashrrev_i32_e32 v11, 31, v10
	ds_read_b128 v[6:9], v3
	v_lshlrev_b64 v[10:11], 20, v[10:11]
	s_lshl_b64 s[46:47], s[44:45], 15
	v_lshl_add_u64 v[10:11], s[28:29], 0, v[10:11]
	v_lshlrev_b32_e32 v4, 7, v4
	v_lshl_add_u64 v[10:11], v[10:11], 0, s[46:47]
	v_and_b32_e32 v4, 0x7f80, v4
	v_mov_b32_e32 v5, v0
	v_lshl_add_u64 v[4:5], v[10:11], 0, v[4:5]
	v_lshl_add_u64 v[4:5], v[68:69], 1, v[4:5]
	s_waitcnt lgkmcnt(0)
	global_store_dwordx4 v[4:5], v[6:9], off nt
.LBB0_1170:
	s_or_b64 exec, exec, s[2:3]
	v_add_u32_e32 v4, 8, v2
	v_ashrrev_i32_e32 v5, 31, v4
	v_lshrrev_b32_e32 v5, 25, v5
	v_add_u32_e32 v5, v4, v5
	v_lshlrev_b32_e32 v6, 1, v5
	v_and_b32_e32 v5, 0xffffff80, v5
	v_and_b32_e32 v6, 0xffffff00, v6
	v_sub_u32_e32 v4, v4, v5
	v_add_u32_e32 v5, v6, v4
	v_cmp_gt_i32_e32 vcc, s84, v5
	s_and_saveexec_b64 s[2:3], vcc
	s_cbranch_execz .LBB0_1172
	v_or_b32_e32 v6, 8, v1
	v_lshlrev_b32_e32 v7, 7, v6
	v_lshrrev_b32_e32 v6, 2, v6
	v_xor_b32_e32 v6, v6, v194
	v_lshlrev_b32_e32 v6, 4, v6
	v_and_b32_e32 v6, 0x70, v6
	v_ashrrev_i32_e32 v10, 8, v5
	v_add3_u32 v6, 0, v7, v6
	v_ashrrev_i32_e32 v11, 31, v10
	ds_read_b128 v[6:9], v6
	v_lshlrev_b64 v[10:11], 20, v[10:11]
	s_lshl_b64 s[46:47], s[44:45], 15
	v_lshl_add_u64 v[10:11], s[28:29], 0, v[10:11]
	v_lshlrev_b32_e32 v4, 7, v4
	v_lshl_add_u64 v[10:11], v[10:11], 0, s[46:47]
	v_and_b32_e32 v4, 0x7f80, v4
	v_mov_b32_e32 v5, v0
	v_lshl_add_u64 v[4:5], v[10:11], 0, v[4:5]
	v_lshl_add_u64 v[4:5], v[68:69], 1, v[4:5]
	s_waitcnt lgkmcnt(0)
	global_store_dwordx4 v[4:5], v[6:9], off nt
.LBB0_1172:
	s_or_b64 exec, exec, s[2:3]
	v_add_u32_e32 v4, 16, v2
	v_ashrrev_i32_e32 v5, 31, v4
	v_lshrrev_b32_e32 v5, 25, v5
	v_add_u32_e32 v5, v4, v5
	v_lshlrev_b32_e32 v6, 1, v5
	v_and_b32_e32 v5, 0xffffff80, v5
	v_and_b32_e32 v6, 0xffffff00, v6
	v_sub_u32_e32 v4, v4, v5
	v_add_u32_e32 v5, v6, v4
	v_cmp_gt_i32_e32 vcc, s84, v5
	s_and_saveexec_b64 s[2:3], vcc
	s_cbranch_execz .LBB0_1174
	v_or_b32_e32 v6, 16, v1
	v_lshlrev_b32_e32 v7, 7, v6
	v_lshrrev_b32_e32 v6, 2, v6
	v_xor_b32_e32 v6, v6, v194
	v_lshlrev_b32_e32 v6, 4, v6
	v_and_b32_e32 v6, 0x70, v6
	v_ashrrev_i32_e32 v10, 8, v5
	v_add3_u32 v6, 0, v7, v6
	v_ashrrev_i32_e32 v11, 31, v10
	ds_read_b128 v[6:9], v6
	v_lshlrev_b64 v[10:11], 20, v[10:11]
	s_lshl_b64 s[46:47], s[44:45], 15
	v_lshl_add_u64 v[10:11], s[28:29], 0, v[10:11]
	v_lshlrev_b32_e32 v4, 7, v4
	v_lshl_add_u64 v[10:11], v[10:11], 0, s[46:47]
	v_and_b32_e32 v4, 0x7f80, v4
	v_mov_b32_e32 v5, v0
	v_lshl_add_u64 v[4:5], v[10:11], 0, v[4:5]
	v_lshl_add_u64 v[4:5], v[68:69], 1, v[4:5]
	s_waitcnt lgkmcnt(0)
	global_store_dwordx4 v[4:5], v[6:9], off nt
; #define LAS __attribute__((address_space(3)))
; __device__ __forceinline__ void cvt_tile(const float* W, int ldw, int nvalid, int k0, int n0, bf16_t* WT, int K, int map, int rows_cap, LAS unsigned char* T, int tid, const float* gvec) {
;     ...
;     for (int it = 0; it < 8; ++it) { const int n = 64 * w + 8 * it + (lane >> 3), c = lane & 7;
;         const u32x4 o = *(const LAS u32x4*)(T + n * 128 + ((c ^ ((n >> 2) & 7)) << 4));
;         const int ng = n0 + n; const int d = map == 0 ? ng : (ng / 128) * 256 + (ng % 128) + (map == 2 ? 128 : 0);
;         if (d < rows_cap) *(u32x4*)(WT + ((size_t)(d >> 8) * nkt + kt) * 16384 + (d & 255) * 64 + 8 * c) = o; }
;     __syncthreads();
.LBB0_1174:
	s_or_b64 exec, exec, s[2:3]
	v_add_u32_e32 v4, 24, v2
	v_ashrrev_i32_e32 v5, 31, v4
	v_lshrrev_b32_e32 v5, 25, v5
	v_add_u32_e32 v5, v4, v5
	v_lshlrev_b32_e32 v6, 1, v5
	v_and_b32_e32 v5, 0xffffff80, v5
	v_and_b32_e32 v6, 0xffffff00, v6
	v_sub_u32_e32 v4, v4, v5
	v_add_u32_e32 v5, v6, v4
	v_cmp_gt_i32_e32 vcc, s84, v5
	s_and_saveexec_b64 s[2:3], vcc
	s_cbranch_execz .LBB0_1176
	v_or_b32_e32 v6, 24, v1
	v_lshlrev_b32_e32 v7, 7, v6
	v_lshrrev_b32_e32 v6, 2, v6
	v_xor_b32_e32 v6, v6, v194
	v_lshlrev_b32_e32 v6, 4, v6
	v_and_b32_e32 v6, 0x70, v6
	v_ashrrev_i32_e32 v10, 8, v5
	v_add3_u32 v6, 0, v7, v6
	v_ashrrev_i32_e32 v11, 31, v10
	ds_read_b128 v[6:9], v6
	v_lshlrev_b64 v[10:11], 20, v[10:11]
	s_lshl_b64 s[46:47], s[44:45], 15
	v_lshl_add_u64 v[10:11], s[28:29], 0, v[10:11]
	v_lshlrev_b32_e32 v4, 7, v4
	v_lshl_add_u64 v[10:11], v[10:11], 0, s[46:47]
	v_and_b32_e32 v4, 0x7f80, v4
	v_mov_b32_e32 v5, v0
	v_lshl_add_u64 v[4:5], v[10:11], 0, v[4:5]
	v_lshl_add_u64 v[4:5], v[68:69], 1, v[4:5]
	s_waitcnt lgkmcnt(0)
	global_store_dwordx4 v[4:5], v[6:9], off nt
.LBB0_1176:
	s_or_b64 exec, exec, s[2:3]
	v_add_u32_e32 v4, 32, v2
	v_ashrrev_i32_e32 v5, 31, v4
	v_lshrrev_b32_e32 v5, 25, v5
	v_add_u32_e32 v5, v4, v5
	v_lshlrev_b32_e32 v6, 1, v5
	v_and_b32_e32 v5, 0xffffff80, v5
	v_and_b32_e32 v6, 0xffffff00, v6
	v_sub_u32_e32 v4, v4, v5
	v_add_u32_e32 v5, v6, v4
	v_cmp_gt_i32_e32 vcc, s84, v5
	s_and_saveexec_b64 s[2:3], vcc
	s_cbranch_execz .LBB0_1178
	v_ashrrev_i32_e32 v10, 8, v5
	v_ashrrev_i32_e32 v11, 31, v10
	ds_read_b128 v[6:9], v3 offset:4096
	v_lshlrev_b64 v[10:11], 20, v[10:11]
	s_lshl_b64 s[46:47], s[44:45], 15
	v_lshl_add_u64 v[10:11], s[28:29], 0, v[10:11]
	v_lshlrev_b32_e32 v3, 7, v4
	v_lshl_add_u64 v[10:11], v[10:11], 0, s[46:47]
	v_and_b32_e32 v4, 0x7f80, v3
	v_mov_b32_e32 v5, v0
	v_lshl_add_u64 v[4:5], v[10:11], 0, v[4:5]
	v_lshl_add_u64 v[4:5], v[68:69], 1, v[4:5]
	s_waitcnt lgkmcnt(0)
	global_store_dwordx4 v[4:5], v[6:9], off nt
.LBB0_1178:
	s_or_b64 exec, exec, s[2:3]
	v_add_u32_e32 v3, 40, v2
	v_ashrrev_i32_e32 v4, 31, v3
	v_lshrrev_b32_e32 v4, 25, v4
	v_add_u32_e32 v4, v3, v4
	v_lshlrev_b32_e32 v5, 1, v4
	v_and_b32_e32 v4, 0xffffff80, v4
	v_and_b32_e32 v5, 0xffffff00, v5
	v_sub_u32_e32 v3, v3, v4
	v_add_u32_e32 v4, v5, v3
	v_cmp_gt_i32_e32 vcc, s84, v4
	s_and_saveexec_b64 s[2:3], vcc
	s_cbranch_execz .LBB0_1180
	v_or_b32_e32 v5, 40, v1
	v_lshlrev_b32_e32 v6, 7, v5
	v_lshrrev_b32_e32 v5, 2, v5
	v_xor_b32_e32 v5, v5, v194
	v_lshlrev_b32_e32 v5, 4, v5
	v_and_b32_e32 v5, 0x70, v5
	v_add3_u32 v5, 0, v6, v5
	v_ashrrev_i32_e32 v4, 8, v4
	ds_read_b128 v[6:9], v5
	v_ashrrev_i32_e32 v5, 31, v4
	v_lshlrev_b64 v[4:5], 20, v[4:5]
	s_lshl_b64 s[46:47], s[44:45], 15
	v_lshl_add_u64 v[4:5], s[28:29], 0, v[4:5]
	v_lshlrev_b32_e32 v3, 7, v3
	v_lshl_add_u64 v[4:5], v[4:5], 0, s[46:47]
	v_and_b32_e32 v10, 0x7f80, v3
	v_mov_b32_e32 v11, v0
	v_lshl_add_u64 v[4:5], v[4:5], 0, v[10:11]
	v_lshl_add_u64 v[4:5], v[68:69], 1, v[4:5]
	s_waitcnt lgkmcnt(0)
	global_store_dwordx4 v[4:5], v[6:9], off nt
.LBB0_1180:
	s_or_b64 exec, exec, s[2:3]
	v_add_u32_e32 v3, 48, v2
	v_ashrrev_i32_e32 v4, 31, v3
	v_lshrrev_b32_e32 v4, 25, v4
	v_add_u32_e32 v4, v3, v4
	v_lshlrev_b32_e32 v5, 1, v4
	v_and_b32_e32 v4, 0xffffff80, v4
	v_and_b32_e32 v5, 0xffffff00, v5
	v_sub_u32_e32 v3, v3, v4
	v_add_u32_e32 v4, v5, v3
	v_cmp_gt_i32_e32 vcc, s84, v4
	s_and_saveexec_b64 s[2:3], vcc
	s_cbranch_execz .LBB0_1182
	v_or_b32_e32 v5, 48, v1
	v_lshlrev_b32_e32 v6, 7, v5
	v_lshrrev_b32_e32 v5, 2, v5
	v_xor_b32_e32 v5, v5, v194
	v_lshlrev_b32_e32 v5, 4, v5
	v_and_b32_e32 v5, 0x70, v5
	v_add3_u32 v5, 0, v6, v5
	v_ashrrev_i32_e32 v4, 8, v4
	ds_read_b128 v[6:9], v5
	v_ashrrev_i32_e32 v5, 31, v4
	v_lshlrev_b64 v[4:5], 20, v[4:5]
	s_lshl_b64 s[46:47], s[44:45], 15
	v_lshl_add_u64 v[4:5], s[28:29], 0, v[4:5]
	v_lshlrev_b32_e32 v3, 7, v3
	v_lshl_add_u64 v[4:5], v[4:5], 0, s[46:47]
	v_and_b32_e32 v10, 0x7f80, v3
	v_mov_b32_e32 v11, v0
	v_lshl_add_u64 v[4:5], v[4:5], 0, v[10:11]
	v_lshl_add_u64 v[4:5], v[68:69], 1, v[4:5]
	s_waitcnt lgkmcnt(0)
	global_store_dwordx4 v[4:5], v[6:9], off nt
.LBB0_1182:
	s_or_b64 exec, exec, s[2:3]
	v_add_u32_e32 v2, 56, v2
	v_ashrrev_i32_e32 v3, 31, v2
	v_lshrrev_b32_e32 v3, 25, v3
	v_add_u32_e32 v3, v2, v3
	v_lshlrev_b32_e32 v4, 1, v3
	v_and_b32_e32 v3, 0xffffff80, v3
	v_and_b32_e32 v4, 0xffffff00, v4
	v_sub_u32_e32 v2, v2, v3
	v_add_u32_e32 v3, v4, v2
	v_cmp_gt_i32_e32 vcc, s84, v3
	s_and_saveexec_b64 s[2:3], vcc
	s_cbranch_execz .LBB0_1133
	v_or_b32_e32 v1, 56, v1
	v_lshlrev_b32_e32 v4, 7, v1
	v_lshrrev_b32_e32 v1, 2, v1
	v_xor_b32_e32 v1, v1, v194
	v_lshlrev_b32_e32 v1, 4, v1
	v_and_b32_e32 v1, 0x70, v1
	v_ashrrev_i32_e32 v8, 8, v3
	v_add3_u32 v1, 0, v4, v1
	v_ashrrev_i32_e32 v9, 31, v8
	ds_read_b128 v[4:7], v1
	v_lshlrev_b64 v[8:9], 20, v[8:9]
	s_lshl_b64 s[44:45], s[44:45], 15
	v_lshl_add_u64 v[8:9], s[28:29], 0, v[8:9]
	v_lshlrev_b32_e32 v1, 7, v2
	v_lshl_add_u64 v[8:9], v[8:9], 0, s[44:45]
	v_and_b32_e32 v2, 0x7f80, v1
	v_mov_b32_e32 v3, v0
	v_lshl_add_u64 v[2:3], v[8:9], 0, v[2:3]
	v_lshl_add_u64 v[2:3], v[68:69], 1, v[2:3]
	s_waitcnt lgkmcnt(0)
	global_store_dwordx4 v[2:3], v[4:7], off nt
	s_branch .LBB0_1133

; #define LAS __attribute__((address_space(3)))
; __device__ __forceinline__ unsigned cvt_pk_bf16(float lo, float hi) { f32x2 v = {lo, hi}; bf16x2_t b = __builtin_convertvector(v, bf16x2_t); return __builtin_bit_cast(unsigned, b); }
; __device__ __forceinline__ void cvt_tile(const float* W, int ldw, int nvalid, int k0, int n0, bf16_t* WT, int K, int map, int rows_cap, LAS unsigned char* T, int tid, const float* gvec) {
;     ...
;     const int phys = w ^ (lane & 7);
; #pragma unroll
;     for (int hh = 0; hh < 2; ++hh)
; #pragma unroll
;         for (int r = 0; r < 4; ++r)
; #pragma unroll
;             for (int jn = 0; jn < 4; ++jn) *(LAS unsigned*)(T + (256 * hh + 4 * lane + jn) * 128 + phys * 16 + r * 4) = cvt_pk_bf16(v[hh][2 * r][jn], v[hh][2 * r + 1][jn]);
;     __syncthreads();
;     const int kt = k0 >> 6, nkt = K >> 6;
; #pragma unroll
;     for (int it = 0; it < 8; ++it) { const int n = 64 * w + 8 * it + (lane >> 3), c = lane & 7;
;         const u32x4 o = *(const LAS u32x4*)(T + n * 128 + ((c ^ ((n >> 2) & 7)) << 4));
;         const int ng = n0 + n; const int d = map == 0 ? ng : (ng / 128) * 256 + (ng % 128) + (map == 2 ? 128 : 0);
;         if (d < rows_cap) *(u32x4*)(WT + ((size_t)(d >> 8) * nkt + kt) * 16384 + (d & 255) * 64 + 8 * c) = o; }
;     __syncthreads();
.LBB0_1221:
	v_xor_b32_e32 v1, s51, v79
	s_waitcnt vmcnt(0)
	v_cvt_pk_bf16_f32 v2, v4, v8
	v_lshl_add_u32 v1, v1, 4, v82
	v_cvt_pk_bf16_f32 v8, v5, v9
	v_cvt_pk_bf16_f32 v84, v6, v10
	v_cvt_pk_bf16_f32 v88, v7, v11
	v_cvt_pk_bf16_f32 v3, v12, v16
	v_cvt_pk_bf16_f32 v9, v13, v17
	v_cvt_pk_bf16_f32 v4, v20, v28
	v_cvt_pk_bf16_f32 v10, v21, v29
	v_cvt_pk_bf16_f32 v5, v24, v32
	v_cvt_pk_bf16_f32 v11, v25, v33
	v_cvt_pk_bf16_f32 v85, v14, v18
	v_cvt_pk_bf16_f32 v89, v15, v19
	v_cvt_pk_bf16_f32 v86, v22, v30
	v_cvt_pk_bf16_f32 v90, v23, v31
	ds_write_b128 v1, v[2:5]
	ds_write_b128 v1, v[8:11] offset:128
	v_cvt_pk_bf16_f32 v87, v26, v34
	v_cvt_pk_bf16_f32 v91, v27, v35
	v_cvt_pk_bf16_f32 v2, v36, v40
	v_cvt_pk_bf16_f32 v6, v37, v41
	v_cvt_pk_bf16_f32 v10, v38, v42
	v_cvt_pk_bf16_f32 v14, v39, v43
	v_cvt_pk_bf16_f32 v3, v44, v48
	v_cvt_pk_bf16_f32 v7, v45, v49
	v_cvt_pk_bf16_f32 v11, v46, v50
	v_cvt_pk_bf16_f32 v15, v47, v51
	v_cvt_pk_bf16_f32 v4, v52, v60
	v_cvt_pk_bf16_f32 v8, v53, v61
	v_cvt_pk_bf16_f32 v12, v54, v62
	v_cvt_pk_bf16_f32 v16, v55, v63
	v_cvt_pk_bf16_f32 v5, v56, v64
	v_cvt_pk_bf16_f32 v9, v57, v65
	v_cvt_pk_bf16_f32 v13, v58, v66
	v_cvt_pk_bf16_f32 v17, v59, v67
	s_and_b32 s2, s43, 0xffffffc0
	s_mul_i32 s3, s42, 0x1600
	ds_write_b128 v1, v[84:87] offset:256
	ds_write_b128 v1, v[88:91] offset:384
	ds_write_b128 v1, v[2:5] offset:32768
	ds_write_b128 v1, v[6:9] offset:32896
	ds_write_b128 v1, v[10:13] offset:33024
	ds_write_b128 v1, v[14:17] offset:33152
	v_or_b32_e32 v1, s2, v80
	s_sub_i32 s2, s2, s3
	s_add_i32 s2, s2, s49
	v_add_u32_e32 v2, s2, v80
	v_ashrrev_i32_e32 v3, 31, v2
	v_lshrrev_b32_e32 v3, 25, v3
	v_add_u32_e32 v3, v2, v3
	v_lshlrev_b32_e32 v4, 1, v3
	v_and_b32_e32 v3, 0xffffff80, v3
	v_sub_u32_e32 v3, v2, v3
	v_and_b32_e32 v5, 0xffffff00, v4
	v_add_u32_e32 v4, 0x80, v3
	v_add_u32_e32 v5, v4, v5
	s_ashr_i32 s43, s42, 31
	v_cmp_gt_i32_e32 vcc, s84, v5
	v_lshl_add_u32 v3, v1, 7, v81
	s_waitcnt lgkmcnt(0)
	s_barrier
	s_and_saveexec_b64 s[2:3], vcc
	s_cbranch_execz .LBB0_1223
	v_ashrrev_i32_e32 v10, 8, v5
	v_ashrrev_i32_e32 v11, 31, v10
	ds_read_b128 v[6:9], v3
	v_lshlrev_b64 v[10:11], 20, v[10:11]
	s_lshl_b64 s[44:45], s[42:43], 15
	v_lshl_add_u64 v[10:11], s[28:29], 0, v[10:11]
	v_lshlrev_b32_e32 v4, 7, v4
	v_lshl_add_u64 v[10:11], v[10:11], 0, s[44:45]
	v_and_b32_e32 v4, 0x7f80, v4
	v_mov_b32_e32 v5, v0
	v_lshl_add_u64 v[4:5], v[10:11], 0, v[4:5]
	v_lshl_add_u64 v[4:5], v[68:69], 1, v[4:5]
	s_waitcnt lgkmcnt(0)
	global_store_dwordx4 v[4:5], v[6:9], off nt
.LBB0_1223:
	s_or_b64 exec, exec, s[2:3]
	v_add_u32_e32 v4, 8, v2
	v_ashrrev_i32_e32 v5, 31, v4
	v_lshrrev_b32_e32 v5, 25, v5
	v_add_u32_e32 v5, v4, v5
	v_lshlrev_b32_e32 v6, 1, v5
	v_and_b32_e32 v5, 0xffffff80, v5
	v_sub_u32_e32 v4, v4, v5
	v_and_b32_e32 v6, 0xffffff00, v6
	v_add_u32_e32 v4, 0x80, v4
	v_add_u32_e32 v5, v4, v6
	v_cmp_gt_i32_e32 vcc, s84, v5
	s_and_saveexec_b64 s[2:3], vcc
	s_cbranch_execz .LBB0_1225
	v_or_b32_e32 v6, 8, v1
	v_lshlrev_b32_e32 v7, 7, v6
	v_lshrrev_b32_e32 v6, 2, v6
	v_xor_b32_e32 v6, v6, v194
	v_lshlrev_b32_e32 v6, 4, v6
	v_and_b32_e32 v6, 0x70, v6
	v_ashrrev_i32_e32 v10, 8, v5
	v_add3_u32 v6, 0, v7, v6
	v_ashrrev_i32_e32 v11, 31, v10
	ds_read_b128 v[6:9], v6
	v_lshlrev_b64 v[10:11], 20, v[10:11]
	s_lshl_b64 s[44:45], s[42:43], 15
	v_lshl_add_u64 v[10:11], s[28:29], 0, v[10:11]
	v_lshlrev_b32_e32 v4, 7, v4
	v_lshl_add_u64 v[10:11], v[10:11], 0, s[44:45]
	v_and_b32_e32 v4, 0x7f80, v4
	v_mov_b32_e32 v5, v0
	v_lshl_add_u64 v[4:5], v[10:11], 0, v[4:5]
	v_lshl_add_u64 v[4:5], v[68:69], 1, v[4:5]
	s_waitcnt lgkmcnt(0)
	global_store_dwordx4 v[4:5], v[6:9], off nt
.LBB0_1225:
	s_or_b64 exec, exec, s[2:3]
	v_add_u32_e32 v4, 16, v2
	v_ashrrev_i32_e32 v5, 31, v4
	v_lshrrev_b32_e32 v5, 25, v5
	v_add_u32_e32 v5, v4, v5
	v_lshlrev_b32_e32 v6, 1, v5
	v_and_b32_e32 v5, 0xffffff80, v5
	v_sub_u32_e32 v4, v4, v5
	v_and_b32_e32 v6, 0xffffff00, v6
	v_add_u32_e32 v4, 0x80, v4
	v_add_u32_e32 v5, v4, v6
	v_cmp_gt_i32_e32 vcc, s84, v5
	s_and_saveexec_b64 s[2:3], vcc
	s_cbranch_execz .LBB0_1227
	v_or_b32_e32 v6, 16, v1
	v_lshlrev_b32_e32 v7, 7, v6
	v_lshrrev_b32_e32 v6, 2, v6
	v_xor_b32_e32 v6, v6, v194
	v_lshlrev_b32_e32 v6, 4, v6
	v_and_b32_e32 v6, 0x70, v6
	v_ashrrev_i32_e32 v10, 8, v5
	v_add3_u32 v6, 0, v7, v6
	v_ashrrev_i32_e32 v11, 31, v10
	ds_read_b128 v[6:9], v6
	v_lshlrev_b64 v[10:11], 20, v[10:11]
	s_lshl_b64 s[44:45], s[42:43], 15
	v_lshl_add_u64 v[10:11], s[28:29], 0, v[10:11]
	v_lshlrev_b32_e32 v4, 7, v4
	v_lshl_add_u64 v[10:11], v[10:11], 0, s[44:45]
	v_and_b32_e32 v4, 0x7f80, v4
	v_mov_b32_e32 v5, v0
	v_lshl_add_u64 v[4:5], v[10:11], 0, v[4:5]
	v_lshl_add_u64 v[4:5], v[68:69], 1, v[4:5]
	s_waitcnt lgkmcnt(0)
	global_store_dwordx4 v[4:5], v[6:9], off nt
; #define LAS __attribute__((address_space(3)))
; __device__ __forceinline__ void cvt_tile(const float* W, int ldw, int nvalid, int k0, int n0, bf16_t* WT, int K, int map, int rows_cap, LAS unsigned char* T, int tid, const float* gvec) {
;     ...
;     for (int it = 0; it < 8; ++it) { const int n = 64 * w + 8 * it + (lane >> 3), c = lane & 7;
;         const u32x4 o = *(const LAS u32x4*)(T + n * 128 + ((c ^ ((n >> 2) & 7)) << 4));
;         const int ng = n0 + n; const int d = map == 0 ? ng : (ng / 128) * 256 + (ng % 128) + (map == 2 ? 128 : 0);
;         if (d < rows_cap) *(u32x4*)(WT + ((size_t)(d >> 8) * nkt + kt) * 16384 + (d & 255) * 64 + 8 * c) = o; }
;     __syncthreads();
.LBB0_1227:
	s_or_b64 exec, exec, s[2:3]
	v_add_u32_e32 v4, 24, v2
	v_ashrrev_i32_e32 v5, 31, v4
	v_lshrrev_b32_e32 v5, 25, v5
	v_add_u32_e32 v5, v4, v5
	v_lshlrev_b32_e32 v6, 1, v5
	v_and_b32_e32 v5, 0xffffff80, v5
	v_sub_u32_e32 v4, v4, v5
	v_and_b32_e32 v6, 0xffffff00, v6
	v_add_u32_e32 v4, 0x80, v4
	v_add_u32_e32 v5, v4, v6
	v_cmp_gt_i32_e32 vcc, s84, v5
	s_and_saveexec_b64 s[2:3], vcc
	s_cbranch_execz .LBB0_1229
	v_or_b32_e32 v6, 24, v1
	v_lshlrev_b32_e32 v7, 7, v6
	v_lshrrev_b32_e32 v6, 2, v6
	v_xor_b32_e32 v6, v6, v194
	v_lshlrev_b32_e32 v6, 4, v6
	v_and_b32_e32 v6, 0x70, v6
	v_ashrrev_i32_e32 v10, 8, v5
	v_add3_u32 v6, 0, v7, v6
	v_ashrrev_i32_e32 v11, 31, v10
	ds_read_b128 v[6:9], v6
	v_lshlrev_b64 v[10:11], 20, v[10:11]
	s_lshl_b64 s[44:45], s[42:43], 15
	v_lshl_add_u64 v[10:11], s[28:29], 0, v[10:11]
	v_lshlrev_b32_e32 v4, 7, v4
	v_lshl_add_u64 v[10:11], v[10:11], 0, s[44:45]
	v_and_b32_e32 v4, 0x7f80, v4
	v_mov_b32_e32 v5, v0
	v_lshl_add_u64 v[4:5], v[10:11], 0, v[4:5]
	v_lshl_add_u64 v[4:5], v[68:69], 1, v[4:5]
	s_waitcnt lgkmcnt(0)
	global_store_dwordx4 v[4:5], v[6:9], off nt
.LBB0_1229:
	s_or_b64 exec, exec, s[2:3]
	v_add_u32_e32 v4, 32, v2
	v_ashrrev_i32_e32 v5, 31, v4
	v_lshrrev_b32_e32 v5, 25, v5
	v_add_u32_e32 v5, v4, v5
	v_lshlrev_b32_e32 v6, 1, v5
	v_and_b32_e32 v5, 0xffffff80, v5
	v_sub_u32_e32 v4, v4, v5
	v_and_b32_e32 v6, 0xffffff00, v6
	v_add_u32_e32 v4, 0x80, v4
	v_add_u32_e32 v5, v4, v6
	v_cmp_gt_i32_e32 vcc, s84, v5
	s_and_saveexec_b64 s[2:3], vcc
	s_cbranch_execz .LBB0_1231
	v_ashrrev_i32_e32 v10, 8, v5
	v_ashrrev_i32_e32 v11, 31, v10
	ds_read_b128 v[6:9], v3 offset:4096
	v_lshlrev_b64 v[10:11], 20, v[10:11]
	s_lshl_b64 s[44:45], s[42:43], 15
	v_lshl_add_u64 v[10:11], s[28:29], 0, v[10:11]
	v_lshlrev_b32_e32 v3, 7, v4
	v_lshl_add_u64 v[10:11], v[10:11], 0, s[44:45]
	v_and_b32_e32 v4, 0x7f80, v3
	v_mov_b32_e32 v5, v0
	v_lshl_add_u64 v[4:5], v[10:11], 0, v[4:5]
	v_lshl_add_u64 v[4:5], v[68:69], 1, v[4:5]
	s_waitcnt lgkmcnt(0)
	global_store_dwordx4 v[4:5], v[6:9], off nt
.LBB0_1231:
	s_or_b64 exec, exec, s[2:3]
	v_add_u32_e32 v3, 40, v2
	v_ashrrev_i32_e32 v4, 31, v3
	v_lshrrev_b32_e32 v4, 25, v4
	v_add_u32_e32 v4, v3, v4
	v_lshlrev_b32_e32 v5, 1, v4
	v_and_b32_e32 v4, 0xffffff80, v4
	v_sub_u32_e32 v3, v3, v4
	v_and_b32_e32 v5, 0xffffff00, v5
	v_add_u32_e32 v3, 0x80, v3
	v_add_u32_e32 v4, v3, v5
	v_cmp_gt_i32_e32 vcc, s84, v4
	s_and_saveexec_b64 s[2:3], vcc
	s_cbranch_execz .LBB0_1233
	v_or_b32_e32 v5, 40, v1
	v_lshlrev_b32_e32 v6, 7, v5
	v_lshrrev_b32_e32 v5, 2, v5
	v_xor_b32_e32 v5, v5, v194
	v_lshlrev_b32_e32 v5, 4, v5
	v_and_b32_e32 v5, 0x70, v5
	v_add3_u32 v5, 0, v6, v5
	v_ashrrev_i32_e32 v4, 8, v4
	ds_read_b128 v[6:9], v5
	v_ashrrev_i32_e32 v5, 31, v4
	v_lshlrev_b64 v[4:5], 20, v[4:5]
	s_lshl_b64 s[44:45], s[42:43], 15
	v_lshl_add_u64 v[4:5], s[28:29], 0, v[4:5]
	v_lshlrev_b32_e32 v3, 7, v3
	v_lshl_add_u64 v[4:5], v[4:5], 0, s[44:45]
	v_and_b32_e32 v10, 0x7f80, v3
	v_mov_b32_e32 v11, v0
	v_lshl_add_u64 v[4:5], v[4:5], 0, v[10:11]
	v_lshl_add_u64 v[4:5], v[68:69], 1, v[4:5]
	s_waitcnt lgkmcnt(0)
	global_store_dwordx4 v[4:5], v[6:9], off nt
.LBB0_1233:
	s_or_b64 exec, exec, s[2:3]
	v_add_u32_e32 v3, 48, v2
	v_ashrrev_i32_e32 v4, 31, v3
	v_lshrrev_b32_e32 v4, 25, v4
	v_add_u32_e32 v4, v3, v4
	v_lshlrev_b32_e32 v5, 1, v4
	v_and_b32_e32 v4, 0xffffff80, v4
	v_sub_u32_e32 v3, v3, v4
	v_and_b32_e32 v5, 0xffffff00, v5
	v_add_u32_e32 v3, 0x80, v3
	v_add_u32_e32 v4, v3, v5
	v_cmp_gt_i32_e32 vcc, s84, v4
	s_and_saveexec_b64 s[2:3], vcc
	s_cbranch_execz .LBB0_1235
	v_or_b32_e32 v5, 48, v1
	v_lshlrev_b32_e32 v6, 7, v5
	v_lshrrev_b32_e32 v5, 2, v5
	v_xor_b32_e32 v5, v5, v194
	v_lshlrev_b32_e32 v5, 4, v5
	v_and_b32_e32 v5, 0x70, v5
	v_add3_u32 v5, 0, v6, v5
	v_ashrrev_i32_e32 v4, 8, v4
	ds_read_b128 v[6:9], v5
	v_ashrrev_i32_e32 v5, 31, v4
	v_lshlrev_b64 v[4:5], 20, v[4:5]
	s_lshl_b64 s[44:45], s[42:43], 15
	v_lshl_add_u64 v[4:5], s[28:29], 0, v[4:5]
	v_lshlrev_b32_e32 v3, 7, v3
	v_lshl_add_u64 v[4:5], v[4:5], 0, s[44:45]
	v_and_b32_e32 v10, 0x7f80, v3
	v_mov_b32_e32 v11, v0
	v_lshl_add_u64 v[4:5], v[4:5], 0, v[10:11]
	v_lshl_add_u64 v[4:5], v[68:69], 1, v[4:5]
	s_waitcnt lgkmcnt(0)
	global_store_dwordx4 v[4:5], v[6:9], off nt
.LBB0_1235:
	s_or_b64 exec, exec, s[2:3]
	v_add_u32_e32 v2, 56, v2
	v_ashrrev_i32_e32 v3, 31, v2
	v_lshrrev_b32_e32 v3, 25, v3
	v_add_u32_e32 v3, v2, v3
	v_lshlrev_b32_e32 v4, 1, v3
	v_and_b32_e32 v3, 0xffffff80, v3
	v_sub_u32_e32 v2, v2, v3
	v_and_b32_e32 v4, 0xffffff00, v4
	v_add_u32_e32 v2, 0x80, v2
	v_add_u32_e32 v3, v2, v4
	v_cmp_gt_i32_e32 vcc, s84, v3
	s_and_saveexec_b64 s[2:3], vcc
	s_cbranch_execz .LBB0_1186
	v_or_b32_e32 v1, 56, v1
	v_lshlrev_b32_e32 v4, 7, v1
	v_lshrrev_b32_e32 v1, 2, v1
	v_xor_b32_e32 v1, v1, v194
	v_lshlrev_b32_e32 v1, 4, v1
	v_and_b32_e32 v1, 0x70, v1
	v_ashrrev_i32_e32 v8, 8, v3
	v_add3_u32 v1, 0, v4, v1
	v_ashrrev_i32_e32 v9, 31, v8
	ds_read_b128 v[4:7], v1
	v_lshlrev_b64 v[8:9], 20, v[8:9]
	s_lshl_b64 s[42:43], s[42:43], 15
	v_lshl_add_u64 v[8:9], s[28:29], 0, v[8:9]
	v_lshlrev_b32_e32 v1, 7, v2
	v_lshl_add_u64 v[8:9], v[8:9], 0, s[42:43]
	v_and_b32_e32 v2, 0x7f80, v1
	v_mov_b32_e32 v3, v0
	v_lshl_add_u64 v[2:3], v[8:9], 0, v[2:3]
	v_lshl_add_u64 v[2:3], v[68:69], 1, v[2:3]
	s_waitcnt lgkmcnt(0)
	global_store_dwordx4 v[2:3], v[4:7], off nt
	s_branch .LBB0_1186

; #define LAS __attribute__((address_space(3)))
; __device__ __forceinline__ unsigned cvt_pk_bf16(float lo, float hi) { f32x2 v = {lo, hi}; bf16x2_t b = __builtin_convertvector(v, bf16x2_t); return __builtin_bit_cast(unsigned, b); }
; __device__ __forceinline__ void cvt_tile(const float* W, int ldw, int nvalid, int k0, int n0, bf16_t* WT, int K, int map, int rows_cap, LAS unsigned char* T, int tid, const float* gvec) {
;     ...
;     const int phys = w ^ (lane & 7);
; #pragma unroll
;     for (int hh = 0; hh < 2; ++hh)
; #pragma unroll
;         for (int r = 0; r < 4; ++r)
; #pragma unroll
;             for (int jn = 0; jn < 4; ++jn) *(LAS unsigned*)(T + (256 * hh + 4 * lane + jn) * 128 + phys * 16 + r * 4) = cvt_pk_bf16(v[hh][2 * r][jn], v[hh][2 * r + 1][jn]);
;     __syncthreads();
;     const int kt = k0 >> 6, nkt = K >> 6;
; #pragma unroll
;     for (int it = 0; it < 8; ++it) { const int n = 64 * w + 8 * it + (lane >> 3), c = lane & 7;
;         const u32x4 o = *(const LAS u32x4*)(T + n * 128 + ((c ^ ((n >> 2) & 7)) << 4));
;         const int ng = n0 + n; const int d = map == 0 ? ng : (ng / 128) * 256 + (ng % 128) + (map == 2 ? 128 : 0);
;         if (d < rows_cap) *(u32x4*)(WT + ((size_t)(d >> 8) * nkt + kt) * 16384 + (d & 255) * 64 + 8 * c) = o; }
;     __syncthreads();
.LBB0_1272:
	s_or_b64 exec, exec, s[2:3]
	v_xor_b32_e32 v1, s47, v79
	s_waitcnt vmcnt(0)
	v_cvt_pk_bf16_f32 v2, v2, v6
	v_lshl_add_u32 v1, v1, 4, v82
	v_cvt_pk_bf16_f32 v6, v3, v7
	v_cvt_pk_bf16_f32 v84, v4, v8
	v_cvt_pk_bf16_f32 v88, v5, v9
	v_cvt_pk_bf16_f32 v3, v14, v10
	v_cvt_pk_bf16_f32 v7, v15, v11
	v_cvt_pk_bf16_f32 v4, v22, v18
	v_cvt_pk_bf16_f32 v8, v23, v19
	v_cvt_pk_bf16_f32 v5, v30, v26
	v_cvt_pk_bf16_f32 v9, v31, v27
	v_cvt_pk_bf16_f32 v85, v16, v12
	v_cvt_pk_bf16_f32 v89, v17, v13
	v_cvt_pk_bf16_f32 v86, v24, v20
	v_cvt_pk_bf16_f32 v90, v25, v21
	ds_write_b128 v1, v[2:5]
	ds_write_b128 v1, v[6:9] offset:128
	v_cvt_pk_bf16_f32 v87, v32, v28
	v_cvt_pk_bf16_f32 v91, v33, v29
	v_cvt_pk_bf16_f32 v2, v34, v38
	v_cvt_pk_bf16_f32 v6, v35, v39
	v_cvt_pk_bf16_f32 v10, v36, v40
	v_cvt_pk_bf16_f32 v14, v37, v41
	v_cvt_pk_bf16_f32 v3, v46, v42
	v_cvt_pk_bf16_f32 v7, v47, v43
	v_cvt_pk_bf16_f32 v11, v48, v44
	v_cvt_pk_bf16_f32 v15, v49, v45
	v_cvt_pk_bf16_f32 v4, v54, v50
	v_cvt_pk_bf16_f32 v8, v55, v51
	v_cvt_pk_bf16_f32 v12, v56, v52
	v_cvt_pk_bf16_f32 v16, v57, v53
	v_cvt_pk_bf16_f32 v5, v62, v58
	v_cvt_pk_bf16_f32 v9, v63, v59
	v_cvt_pk_bf16_f32 v13, v64, v60
	v_cvt_pk_bf16_f32 v17, v65, v61
	s_and_b32 s2, s43, 0xffffffc0
	ds_write_b128 v1, v[84:87] offset:256
	ds_write_b128 v1, v[88:91] offset:384
	ds_write_b128 v1, v[2:5] offset:32768
	ds_write_b128 v1, v[6:9] offset:32896
	ds_write_b128 v1, v[10:13] offset:33024
	ds_write_b128 v1, v[14:17] offset:33152
	v_or_b32_e32 v1, s2, v80
	s_sub_i32 s2, s2, s38
	s_add_i32 s2, s2, s5
	v_add_u32_e32 v2, s2, v80
	s_ashr_i32 s43, s42, 31
	v_cmp_gt_i32_e32 vcc, s72, v2
	v_lshlrev_b32_e32 v3, 7, v1
	s_waitcnt lgkmcnt(0)
	s_barrier
	s_and_saveexec_b64 s[2:3], vcc
	s_cbranch_execz .LBB0_1274
	v_lshrrev_b32_e32 v8, 8, v2
	v_mul_i32_i24_e32 v8, 0x58, v8
	v_add_u32_e32 v4, v81, v3
	v_ashrrev_i32_e32 v9, 31, v8
	ds_read_b128 v[4:7], v4
	v_lshl_add_u64 v[8:9], v[8:9], 0, s[42:43]
	v_lshlrev_b64 v[8:9], 15, v[8:9]
	v_lshl_add_u64 v[8:9], s[28:29], 0, v[8:9]
	v_and_b32_e32 v10, 0x6380, v3
	v_mov_b32_e32 v11, v0
	v_lshl_add_u64 v[8:9], v[8:9], 0, v[10:11]
	v_lshl_add_u64 v[8:9], v[68:69], 1, v[8:9]
	s_waitcnt lgkmcnt(0)
	global_store_dwordx4 v[8:9], v[4:7], off nt
.LBB0_1274:
	s_or_b64 exec, exec, s[2:3]
	s_nop 0
	v_add_u32_e32 v4, 8, v2
	v_cmp_gt_i32_e32 vcc, s72, v4
	s_and_saveexec_b64 s[2:3], vcc
	s_cbranch_execz .LBB0_1276
	v_or_b32_e32 v5, 8, v1
	v_lshlrev_b32_e32 v10, 7, v5
	v_lshrrev_b32_e32 v5, 2, v5
	v_xor_b32_e32 v5, v5, v194
	v_lshlrev_b32_e32 v5, 4, v5
	v_and_b32_e32 v5, 0x70, v5
	v_lshrrev_b32_e32 v4, 8, v4
	v_add3_u32 v5, 0, v10, v5
	v_mul_i32_i24_e32 v4, 0x58, v4
	ds_read_b128 v[6:9], v5
	v_ashrrev_i32_e32 v5, 31, v4
	v_lshl_add_u64 v[4:5], v[4:5], 0, s[42:43]
	v_lshlrev_b64 v[4:5], 15, v[4:5]
	v_lshl_add_u64 v[4:5], s[28:29], 0, v[4:5]
	v_and_b32_e32 v10, 0x6780, v10
	v_mov_b32_e32 v11, v0
	v_lshl_add_u64 v[4:5], v[4:5], 0, v[10:11]
	v_lshl_add_u64 v[4:5], v[68:69], 1, v[4:5]
	s_waitcnt lgkmcnt(0)
	global_store_dwordx4 v[4:5], v[6:9], off nt
.LBB0_1276:
	s_or_b64 exec, exec, s[2:3]
	v_add_u32_e32 v4, 16, v2
	v_cmp_gt_i32_e32 vcc, s72, v4
	s_and_saveexec_b64 s[2:3], vcc
	s_cbranch_execz .LBB0_1278
	v_or_b32_e32 v5, 16, v1
	v_lshlrev_b32_e32 v10, 7, v5
	v_lshrrev_b32_e32 v5, 2, v5
	v_xor_b32_e32 v5, v5, v194
	v_lshlrev_b32_e32 v5, 4, v5
	v_and_b32_e32 v5, 0x70, v5
	v_lshrrev_b32_e32 v4, 8, v4
	v_add3_u32 v5, 0, v10, v5
	v_mul_i32_i24_e32 v4, 0x58, v4
	ds_read_b128 v[6:9], v5
	v_ashrrev_i32_e32 v5, 31, v4
	v_lshl_add_u64 v[4:5], v[4:5], 0, s[42:43]
	v_lshlrev_b64 v[4:5], 15, v[4:5]
	v_lshl_add_u64 v[4:5], s[28:29], 0, v[4:5]
	v_and_b32_e32 v10, 0x6b80, v10
	v_mov_b32_e32 v11, v0
	v_lshl_add_u64 v[4:5], v[4:5], 0, v[10:11]
	v_lshl_add_u64 v[4:5], v[68:69], 1, v[4:5]
	s_waitcnt lgkmcnt(0)
	global_store_dwordx4 v[4:5], v[6:9], off nt
; #define LAS __attribute__((address_space(3)))
; __device__ __forceinline__ void cvt_tile(const float* W, int ldw, int nvalid, int k0, int n0, bf16_t* WT, int K, int map, int rows_cap, LAS unsigned char* T, int tid, const float* gvec) {
;     ...
;     for (int it = 0; it < 8; ++it) { const int n = 64 * w + 8 * it + (lane >> 3), c = lane & 7;
;         const u32x4 o = *(const LAS u32x4*)(T + n * 128 + ((c ^ ((n >> 2) & 7)) << 4));
;         const int ng = n0 + n; const int d = map == 0 ? ng : (ng / 128) * 256 + (ng % 128) + (map == 2 ? 128 : 0);
;         if (d < rows_cap) *(u32x4*)(WT + ((size_t)(d >> 8) * nkt + kt) * 16384 + (d & 255) * 64 + 8 * c) = o; }
;     __syncthreads();
.LBB0_1278:
	s_or_b64 exec, exec, s[2:3]
	v_add_u32_e32 v4, 24, v2
	v_cmp_gt_i32_e32 vcc, s72, v4
	s_and_saveexec_b64 s[2:3], vcc
	s_cbranch_execz .LBB0_1280
	v_or_b32_e32 v5, 24, v1
	v_lshlrev_b32_e32 v10, 7, v5
	v_lshrrev_b32_e32 v5, 2, v5
	v_xor_b32_e32 v5, v5, v194
	v_lshlrev_b32_e32 v5, 4, v5
	v_and_b32_e32 v5, 0x70, v5
	v_lshrrev_b32_e32 v4, 8, v4
	v_add3_u32 v5, 0, v10, v5
	v_mul_i32_i24_e32 v4, 0x58, v4
	ds_read_b128 v[6:9], v5
	v_ashrrev_i32_e32 v5, 31, v4
	v_lshl_add_u64 v[4:5], v[4:5], 0, s[42:43]
	v_lshlrev_b64 v[4:5], 15, v[4:5]
	v_lshl_add_u64 v[4:5], s[28:29], 0, v[4:5]
	v_and_b32_e32 v10, 0x6f80, v10
	v_mov_b32_e32 v11, v0
	v_lshl_add_u64 v[4:5], v[4:5], 0, v[10:11]
	v_lshl_add_u64 v[4:5], v[68:69], 1, v[4:5]
	s_waitcnt lgkmcnt(0)
	global_store_dwordx4 v[4:5], v[6:9], off nt
.LBB0_1280:
	s_or_b64 exec, exec, s[2:3]
	v_add_u32_e32 v4, 32, v2
	v_cmp_gt_i32_e32 vcc, s72, v4
	s_and_saveexec_b64 s[2:3], vcc
	s_cbranch_execz .LBB0_1282
	v_or_b32_e32 v5, 0x1000, v3
	v_lshrrev_b32_e32 v4, 8, v4
	v_add_u32_e32 v5, v81, v5
	v_mul_i32_i24_e32 v4, 0x58, v4
	ds_read_b128 v[6:9], v5
	v_ashrrev_i32_e32 v5, 31, v4
	v_lshl_add_u64 v[4:5], v[4:5], 0, s[42:43]
	v_lshlrev_b64 v[4:5], 15, v[4:5]
	v_lshl_add_u64 v[4:5], s[28:29], 0, v[4:5]
	v_bitop3_b32 v10, v3, s74, v216 bitop3:0xc8
	v_mov_b32_e32 v11, v0
	v_lshl_add_u64 v[4:5], v[4:5], 0, v[10:11]
	v_lshl_add_u64 v[4:5], v[68:69], 1, v[4:5]
	s_waitcnt lgkmcnt(0)
	global_store_dwordx4 v[4:5], v[6:9], off nt
.LBB0_1282:
	s_or_b64 exec, exec, s[2:3]
	v_add_u32_e32 v3, 40, v2
	v_cmp_gt_i32_e32 vcc, s72, v3
	s_and_saveexec_b64 s[2:3], vcc
	s_cbranch_execz .LBB0_1284
	v_or_b32_e32 v4, 40, v1
	v_lshlrev_b32_e32 v10, 7, v4
	v_lshrrev_b32_e32 v4, 2, v4
	v_xor_b32_e32 v4, v4, v194
	v_lshlrev_b32_e32 v4, 4, v4
	v_lshrrev_b32_e32 v3, 8, v3
	v_and_b32_e32 v4, 0x70, v4
	v_mul_i32_i24_e32 v8, 0x58, v3
	v_add3_u32 v4, 0, v10, v4
	v_ashrrev_i32_e32 v9, 31, v8
	ds_read_b128 v[4:7], v4
	v_lshl_add_u64 v[8:9], v[8:9], 0, s[42:43]
	v_lshlrev_b64 v[8:9], 15, v[8:9]
	v_lshl_add_u64 v[8:9], s[28:29], 0, v[8:9]
	v_and_b32_e32 v10, 0x7780, v10
	v_mov_b32_e32 v11, v0
	v_lshl_add_u64 v[8:9], v[8:9], 0, v[10:11]
	v_lshl_add_u64 v[8:9], v[68:69], 1, v[8:9]
	s_waitcnt lgkmcnt(0)
	global_store_dwordx4 v[8:9], v[4:7], off nt
.LBB0_1284:
	s_or_b64 exec, exec, s[2:3]
	v_add_u32_e32 v3, 48, v2
	v_cmp_gt_i32_e32 vcc, s72, v3
	s_and_saveexec_b64 s[2:3], vcc
	s_cbranch_execz .LBB0_1286
	v_or_b32_e32 v4, 48, v1
	v_lshlrev_b32_e32 v10, 7, v4
	v_lshrrev_b32_e32 v4, 2, v4
	v_xor_b32_e32 v4, v4, v194
	v_lshlrev_b32_e32 v4, 4, v4
	v_lshrrev_b32_e32 v3, 8, v3
	v_and_b32_e32 v4, 0x70, v4
	v_mul_i32_i24_e32 v8, 0x58, v3
	v_add3_u32 v4, 0, v10, v4
	v_ashrrev_i32_e32 v9, 31, v8
	ds_read_b128 v[4:7], v4
	v_lshl_add_u64 v[8:9], v[8:9], 0, s[42:43]
	v_lshlrev_b64 v[8:9], 15, v[8:9]
	v_lshl_add_u64 v[8:9], s[28:29], 0, v[8:9]
	v_and_b32_e32 v10, 0x7b80, v10
	v_mov_b32_e32 v11, v0
	v_lshl_add_u64 v[8:9], v[8:9], 0, v[10:11]
	v_lshl_add_u64 v[8:9], v[68:69], 1, v[8:9]
	s_waitcnt lgkmcnt(0)
	global_store_dwordx4 v[8:9], v[4:7], off nt
.LBB0_1286:
	s_or_b64 exec, exec, s[2:3]
	v_add_u32_e32 v2, 56, v2
	v_cmp_gt_i32_e32 vcc, s72, v2
	s_and_saveexec_b64 s[2:3], vcc
	s_cbranch_execz .LBB0_1239
	v_or_b32_e32 v1, 56, v1
	v_lshlrev_b32_e32 v8, 7, v1
	v_lshrrev_b32_e32 v1, 2, v1
	v_xor_b32_e32 v1, v1, v194
	v_lshlrev_b32_e32 v1, 4, v1
	v_and_b32_e32 v1, 0x70, v1
	v_add3_u32 v1, 0, v8, v1
	ds_read_b128 v[4:7], v1
	v_lshrrev_b32_e32 v1, 8, v2
	v_mul_i32_i24_e32 v2, 0x58, v1
	v_ashrrev_i32_e32 v3, 31, v2
	v_lshl_add_u64 v[2:3], v[2:3], 0, s[42:43]
	v_lshlrev_b64 v[2:3], 15, v[2:3]
	v_lshl_add_u64 v[2:3], s[28:29], 0, v[2:3]
	v_and_b32_e32 v8, 0x7f80, v8
	v_mov_b32_e32 v9, v0
	v_lshl_add_u64 v[2:3], v[2:3], 0, v[8:9]
	v_lshl_add_u64 v[2:3], v[68:69], 1, v[2:3]
	s_waitcnt lgkmcnt(0)
	global_store_dwordx4 v[2:3], v[4:7], off nt
	s_branch .LBB0_1239
